# attention loops: second score accumulator v[82:97] (LDS-spilled constants), S(kt1) MFMAs overlap softmax(kt0), PV(kt0) overlaps max(kt1); bit-identical
# speedup vs baseline: 1.0209x; 1.0040x over previous
; DI unsigned f2bf(float f) { unsigned u = __builtin_bit_cast(unsigned, f); return (u + 0x7fffu + ((u >> 16) & 1u)) >> 16; }
; DI float shx(float v, int o, int lane) { return __int_as_float(__builtin_amdgcn_ds_bpermute((lane ^ o) << 2, __float_as_int(v))); }
; DI int crow(int i, int hh) { return (i & 3) + 8 * (i >> 2) + 4 * hh; }
; DI void attn_item(CArgs& a, LAS unsigned char* lds, int l, int b, int h, int qb, int tid_, int wave, int lane_) {
;     ...
;     const float ltot = l_run + shx(l_run, 32, lane);
;     if (hh == 0) scr[r] = 1.f / ltot;
;     asm volatile("s_waitcnt lgkmcnt(0)" ::: "memory");
;     bf16_t* mix = (bf16_t*)(a.ws + WS_BUFA);
;     const size_t trow0 = (size_t)b * S_ + qb * 256 + wave * 32;
; #pragma unroll
;     for (int i = 0; i < 16; ++i) { const float inv = scr[crow(i, hh)]; float s = 0.f;
; #pragma unroll
;         for (int vt = 0; vt < 4; ++vt) { o[vt][i] *= inv; s += o[vt][i] * o[vt][i]; }
;         s += shx(s, 1, lane); s += shx(s, 2, lane); s += shx(s, 4, lane); s += shx(s, 8, lane); s += shx(s, 16, lane);
;         const float rs = rsqrtf(s * (1.f / 128.f) + EPS);
; #pragma unroll
;         for (int vt = 0; vt < 4; ++vt) { const int col = h * 128 + 32 * vt + r; mix[(trow0 + crow(i, hh)) * DM + 1024 + col] = (bf16_t)f2bf(o[vt][i] * rs * a.in[I_MIXG][l * DM + 1024 + col]); } }
.LBB0_294:
	s_or_b64 exec, exec, s[0:1]
	s_waitcnt lgkmcnt(0)
	v_lshl_add_u32 v74, v195, 2, s27
	ds_read_b128 v[76:79], v74
	v_or_b32_e32 v70, s43, v169
	s_or_b32 s0, s14, s5
	v_or_b32_e32 v80, s92, v70
	s_add_u32 s0, s0, s26
	s_waitcnt lgkmcnt(1)
	v_mov_b32_e32 v64, v0
	v_mov_b32_e32 v65, v16
	v_lshl_add_u64 v[106:107], v[80:81], 2, s[8:9]
	s_addc_u32 s1, s15, s40
	s_waitcnt lgkmcnt(0)
	v_pk_mul_f32 v[98:99], v[64:65], v[76:77] op_sel_hi:[1,0]
	v_mov_b32_e32 v64, v48
	v_mov_b32_e32 v65, v32
	v_add_co_u32_e32 v106, vcc, s49, v106
	v_pk_mul_f32 v[102:103], v[64:65], v[76:77] op_sel_hi:[1,0]
	v_or_b32_e32 v64, s0, v195
	v_mov_b32_e32 v65, s1
	v_addc_co_u32_e32 v107, vcc, 0, v107, vcc
	v_lshlrev_b64 v[68:69], 12, v[64:65]
	global_load_dword v48, v[106:107], off
	v_lshl_add_u64 v[68:69], s[12:13], 0, v[68:69]
	v_lshlrev_b32_e32 v80, 1, v70
	v_lshl_add_u64 v[106:107], v[68:69], 0, v[80:81]
	v_add_u32_e32 v68, s92, v70
	v_mov_b32_e32 v69, v81
	v_lshl_add_u64 v[68:69], v[68:69], 2, s[8:9]
	v_add_co_u32_e32 v108, vcc, s49, v68
	v_mov_b32_e32 v16, v1
	s_nop 0
	v_addc_co_u32_e32 v109, vcc, 0, v69, vcc
	global_load_dword v68, v[108:109], off offset:128
	global_load_dword v70, v[108:109], off offset:256
	global_load_dword v69, v[108:109], off offset:384
	v_pk_mul_f32 v[0:1], v[16:17], v[76:77] op_sel:[0,1]
	v_mov_b32_e32 v32, v49
	v_pk_mul_f32 v[100:101], v[98:99], v[98:99]
	v_pk_mul_f32 v[16:17], v[0:1], v[0:1]
	v_pk_mul_f32 v[32:33], v[32:33], v[76:77] op_sel:[0,1]
	v_pk_mul_f32 v[104:105], v[102:103], v[102:103]
	v_pk_mul_f32 v[76:77], v[32:33], v[32:33]
	v_mov_b32_e32 v108, v16
	v_mov_b32_e32 v109, v100
	v_mov_b32_e32 v100, v17
	v_pk_add_f32 v[16:17], v[108:109], v[100:101]
	v_mov_b32_e32 v100, v77
	v_mov_b32_e32 v101, v105
	v_pk_add_f32 v[16:17], v[100:101], v[16:17]
	v_mov_b32_e32 v77, v104
	v_xor_b32_e32 v73, 4, v196
	v_pk_add_f32 v[16:17], v[76:77], v[16:17]
	ds_bpermute_b32 v77, v73, v17
	ds_bpermute_b32 v76, v73, v16
	v_xor_b32_e32 v72, 8, v196
	v_xor_b32_e32 v71, 16, v196
	v_xor_b32_e32 v67, 32, v196
	v_xor_b32_e32 v66, 64, v196
	s_waitcnt lgkmcnt(0)
	v_pk_add_f32 v[16:17], v[16:17], v[76:77]
	ds_bpermute_b32 v77, v72, v17
	ds_bpermute_b32 v76, v72, v16
	v_or_b32_e32 v100, 2, v64
	v_mov_b32_e32 v101, s1
	v_lshlrev_b64 v[100:101], 12, v[100:101]
	v_lshl_add_u64 v[100:101], s[12:13], 0, v[100:101]
	s_waitcnt lgkmcnt(0)
	v_pk_add_f32 v[16:17], v[16:17], v[76:77]
	ds_bpermute_b32 v77, v71, v17
	ds_bpermute_b32 v76, v71, v16
	v_lshl_add_u64 v[100:101], v[100:101], 0, v[80:81]
	s_add_i32 s42, s42, s72
	s_add_i32 s41, s41, s72
	s_cmpk_gt_i32 s42, 0xff
	s_waitcnt lgkmcnt(0)
	v_pk_add_f32 v[16:17], v[16:17], v[76:77]
	ds_bpermute_b32 v77, v67, v17
	ds_bpermute_b32 v76, v67, v16
	s_waitcnt lgkmcnt(0)
	v_pk_add_f32 v[16:17], v[16:17], v[76:77]
	ds_bpermute_b32 v77, v66, v17
	ds_bpermute_b32 v76, v66, v16
	s_waitcnt lgkmcnt(0)
	v_pk_add_f32 v[76:77], v[16:17], v[76:77]
	v_mov_b64_e32 v[16:17], s[76:77]
	v_pk_fma_f32 v[76:77], v[76:77], s[78:79], v[16:17] op_sel_hi:[1,0,0]
	s_nop 0
	v_mul_f32_e32 v49, 0x4b800000, v77
	v_cmp_gt_f32_e64 s[6:7], s64, v77
	v_cmp_gt_f32_e32 vcc, s64, v76
	s_nop 0
	v_cndmask_b32_e64 v49, v77, v49, s[6:7]
	v_rsq_f32_e32 v49, v49
	s_nop 0
	v_mul_f32_e32 v75, 0x45800000, v49
	v_cndmask_b32_e64 v49, v49, v75, s[6:7]
	v_mul_f32_e32 v75, v98, v49
	s_waitcnt vmcnt(3)
	v_mul_f32_e32 v75, v48, v75
	v_bfe_u32 v77, v75, 16, 1
	v_add3_u32 v75, v75, v77, s33
	global_store_short_d16_hi v[106:107], v75, off
	v_mul_f32_e32 v75, v99, v49
	s_waitcnt vmcnt(3)
	v_mul_f32_e32 v75, v68, v75
	v_bfe_u32 v77, v75, 16, 1
	v_add3_u32 v75, v75, v77, s33
	global_store_short_d16_hi v[106:107], v75, off offset:64
	v_mul_f32_e32 v75, v103, v49
	s_waitcnt vmcnt(3)
	v_mul_f32_e32 v75, v70, v75
	v_bfe_u32 v77, v75, 16, 1
	v_mul_f32_e32 v49, v102, v49
	v_add3_u32 v75, v75, v77, s33
	s_waitcnt vmcnt(2)
	v_mul_f32_e32 v49, v69, v49
	global_store_short_d16_hi v[106:107], v75, off offset:128
	v_bfe_u32 v75, v49, 16, 1
	v_add3_u32 v49, v49, v75, s33
	global_store_short_d16_hi v[106:107], v49, off offset:192
	v_mul_f32_e32 v49, 0x4b800000, v76
	v_cndmask_b32_e32 v49, v76, v49, vcc
	v_rsq_f32_e32 v49, v49
	v_or_b32_e32 v76, 1, v64
	v_mov_b32_e32 v77, s1
	v_lshlrev_b64 v[76:77], 12, v[76:77]
	v_mul_f32_e32 v75, 0x45800000, v49
	v_cndmask_b32_e32 v49, v49, v75, vcc
	v_mul_f32_e32 v0, v0, v49
	v_mul_f32_e32 v0, v48, v0
	v_lshl_add_u64 v[76:77], s[12:13], 0, v[76:77]
	v_bfe_u32 v75, v0, 16, 1
	v_add3_u32 v0, v0, v75, s33
	v_lshl_add_u64 v[76:77], v[76:77], 0, v[80:81]
	global_store_short_d16_hi v[76:77], v0, off
	v_mul_f32_e32 v0, v1, v49
	v_mul_f32_e32 v0, v68, v0
	v_bfe_u32 v1, v0, 16, 1
	v_add3_u32 v0, v0, v1, s33
	global_store_short_d16_hi v[76:77], v0, off offset:64
	v_mul_f32_e32 v0, v33, v49
	v_mul_f32_e32 v0, v70, v0
	v_bfe_u32 v1, v0, 16, 1
	v_add3_u32 v0, v0, v1, s33
	global_store_short_d16_hi v[76:77], v0, off offset:128
	v_mul_f32_e32 v0, v32, v49
	v_mul_f32_e32 v0, v69, v0
	v_bfe_u32 v1, v0, 16, 1
	v_add3_u32 v0, v0, v1, s33
	global_store_short_d16_hi v[76:77], v0, off offset:192
	v_mov_b32_e32 v0, v2
	v_mov_b32_e32 v1, v18
	v_mov_b32_e32 v18, v3
	v_mov_b32_e32 v2, v79
	v_pk_mul_f32 v[0:1], v[0:1], v[78:79] op_sel_hi:[1,0]
	v_mov_b32_e32 v76, v50
	v_mov_b32_e32 v77, v34
	v_pk_mul_f32 v[18:19], v[18:19], v[2:3] op_sel_hi:[1,0]
	v_mov_b32_e32 v34, v51
	v_pk_mul_f32 v[32:33], v[0:1], v[0:1]
	v_pk_mul_f32 v[76:77], v[76:77], v[78:79] op_sel_hi:[1,0]
	v_pk_mul_f32 v[78:79], v[18:19], v[18:19]
	v_pk_mul_f32 v[2:3], v[34:35], v[2:3] op_sel_hi:[1,0]
	v_pk_mul_f32 v[98:99], v[76:77], v[76:77]
	v_pk_mul_f32 v[34:35], v[2:3], v[2:3]
	v_mov_b32_e32 v50, v78
	v_mov_b32_e32 v51, v32
	v_mov_b32_e32 v32, v79
	v_pk_add_f32 v[32:33], v[50:51], v[32:33]
	v_mov_b32_e32 v50, v35
	v_mov_b32_e32 v51, v99
	v_pk_add_f32 v[32:33], v[50:51], v[32:33]
	v_mov_b32_e32 v35, v98
	v_pk_add_f32 v[32:33], v[34:35], v[32:33]
	ds_bpermute_b32 v35, v73, v33
	ds_bpermute_b32 v34, v73, v32
	s_waitcnt lgkmcnt(0)
; DI unsigned f2bf(float f) { unsigned u = __builtin_bit_cast(unsigned, f); return (u + 0x7fffu + ((u >> 16) & 1u)) >> 16; }
; DI float shx(float v, int o, int lane) { return __int_as_float(__builtin_amdgcn_ds_bpermute((lane ^ o) << 2, __float_as_int(v))); }
; DI int crow(int i, int hh) { return (i & 3) + 8 * (i >> 2) + 4 * hh; }
; DI void attn_item(CArgs& a, LAS unsigned char* lds, int l, int b, int h, int qb, int tid_, int wave, int lane_) {
;     ...
;     for (int i = 0; i < 16; ++i) { const float inv = scr[crow(i, hh)]; float s = 0.f;
; #pragma unroll
;         for (int vt = 0; vt < 4; ++vt) { o[vt][i] *= inv; s += o[vt][i] * o[vt][i]; }
;         s += shx(s, 1, lane); s += shx(s, 2, lane); s += shx(s, 4, lane); s += shx(s, 8, lane); s += shx(s, 16, lane);
;         const float rs = rsqrtf(s * (1.f / 128.f) + EPS);
; #pragma unroll
;         for (int vt = 0; vt < 4; ++vt) { const int col = h * 128 + 32 * vt + r; mix[(trow0 + crow(i, hh)) * DM + 1024 + col] = (bf16_t)f2bf(o[vt][i] * rs * a.in[I_MIXG][l * DM + 1024 + col]); } }
	v_pk_add_f32 v[32:33], v[32:33], v[34:35]
	ds_bpermute_b32 v35, v72, v33
	ds_bpermute_b32 v34, v72, v32
	s_waitcnt lgkmcnt(0)
	v_pk_add_f32 v[32:33], v[32:33], v[34:35]
	ds_bpermute_b32 v35, v71, v33
	ds_bpermute_b32 v34, v71, v32
	s_waitcnt lgkmcnt(0)
	v_pk_add_f32 v[32:33], v[32:33], v[34:35]
	ds_bpermute_b32 v35, v67, v33
	ds_bpermute_b32 v34, v67, v32
	s_waitcnt lgkmcnt(0)
	v_pk_add_f32 v[32:33], v[32:33], v[34:35]
	ds_bpermute_b32 v35, v66, v33
	ds_bpermute_b32 v34, v66, v32
	s_waitcnt lgkmcnt(0)
	v_pk_add_f32 v[32:33], v[32:33], v[34:35]
	s_nop 0
	v_pk_fma_f32 v[32:33], v[32:33], s[78:79], v[16:17] op_sel_hi:[1,0,0]
	v_mov_b32_e32 v35, v36
	v_mul_f32_e32 v34, 0x4b800000, v33
	v_cmp_gt_f32_e64 s[6:7], s64, v33
	v_cmp_gt_f32_e32 vcc, s64, v32
	v_mov_b32_e32 v36, v53
	v_cndmask_b32_e64 v33, v33, v34, s[6:7]
	v_rsq_f32_e32 v33, v33
	s_nop 0
	v_mul_f32_e32 v34, 0x45800000, v33
	v_cndmask_b32_e64 v33, v33, v34, s[6:7]
	v_mul_f32_e32 v0, v0, v33
	v_mul_f32_e32 v0, v48, v0
	v_bfe_u32 v34, v0, 16, 1
	v_add3_u32 v0, v0, v34, s33
	global_store_short_d16_hi v[100:101], v0, off
	v_mul_f32_e32 v0, v1, v33
	v_mul_f32_e32 v0, v68, v0
	v_bfe_u32 v1, v0, 16, 1
	v_add3_u32 v0, v0, v1, s33
	global_store_short_d16_hi v[100:101], v0, off offset:64
	v_mul_f32_e32 v0, v77, v33
	v_mul_f32_e32 v0, v70, v0
	v_bfe_u32 v1, v0, 16, 1
	v_add3_u32 v0, v0, v1, s33
	global_store_short_d16_hi v[100:101], v0, off offset:128
	v_mul_f32_e32 v0, v76, v33
	v_mul_f32_e32 v0, v69, v0
	v_bfe_u32 v1, v0, 16, 1
	v_add3_u32 v0, v0, v1, s33
	global_store_short_d16_hi v[100:101], v0, off offset:192
	v_mul_f32_e32 v0, 0x4b800000, v32
	v_cndmask_b32_e32 v0, v32, v0, vcc
	v_rsq_f32_e32 v0, v0
	v_mov_b32_e32 v34, v52
	v_or_b32_e32 v76, 8, v64
	v_mov_b32_e32 v77, s1
	v_mul_f32_e32 v1, 0x45800000, v0
	v_cndmask_b32_e32 v32, v0, v1, vcc
	v_or_b32_e32 v0, 3, v64
	v_mov_b32_e32 v1, s1
	v_mul_f32_e32 v18, v18, v32
	v_lshlrev_b64 v[0:1], 12, v[0:1]
	v_mul_f32_e32 v18, v48, v18
	v_lshl_add_u64 v[0:1], s[12:13], 0, v[0:1]
	v_bfe_u32 v33, v18, 16, 1
	v_add3_u32 v18, v18, v33, s33
	v_lshl_add_u64 v[0:1], v[0:1], 0, v[80:81]
	global_store_short_d16_hi v[0:1], v18, off
	v_mul_f32_e32 v18, v19, v32
	v_mul_f32_e32 v18, v68, v18
	v_bfe_u32 v19, v18, 16, 1
	v_mul_f32_e32 v3, v3, v32
	v_add3_u32 v18, v18, v19, s33
	v_mul_f32_e32 v3, v70, v3
	global_store_short_d16_hi v[0:1], v18, off offset:64
	v_bfe_u32 v18, v3, 16, 1
	v_mul_f32_e32 v2, v2, v32
	v_add3_u32 v3, v3, v18, s33
	v_mul_f32_e32 v2, v69, v2
	global_store_short_d16_hi v[0:1], v3, off offset:128
	v_bfe_u32 v3, v2, 16, 1
	v_add3_u32 v2, v2, v3, s33
	global_store_short_d16_hi v[0:1], v2, off offset:192
	ds_read_b128 v[0:3], v74 offset:32
	v_mov_b32_e32 v18, v4
	v_mov_b32_e32 v19, v20
	v_mov_b32_e32 v20, v5
	v_lshlrev_b64 v[76:77], 12, v[76:77]
	s_waitcnt lgkmcnt(0)
	v_pk_mul_f32 v[18:19], v[18:19], v[0:1] op_sel_hi:[1,0]
	v_pk_mul_f32 v[4:5], v[20:21], v[0:1] op_sel:[0,1]
	v_pk_mul_f32 v[32:33], v[18:19], v[18:19]
	v_pk_mul_f32 v[34:35], v[34:35], v[0:1] op_sel_hi:[1,0]
	v_pk_mul_f32 v[20:21], v[4:5], v[4:5]
	v_pk_mul_f32 v[0:1], v[36:37], v[0:1] op_sel:[0,1]
	v_pk_mul_f32 v[50:51], v[34:35], v[34:35]
	v_pk_mul_f32 v[36:37], v[0:1], v[0:1]
	v_mov_b32_e32 v52, v20
	v_mov_b32_e32 v53, v32
	v_mov_b32_e32 v32, v21
	v_pk_add_f32 v[20:21], v[52:53], v[32:33]
	v_mov_b32_e32 v32, v37
	v_mov_b32_e32 v33, v51
	v_pk_add_f32 v[20:21], v[32:33], v[20:21]
	v_mov_b32_e32 v37, v50
	v_pk_add_f32 v[20:21], v[36:37], v[20:21]
	ds_bpermute_b32 v33, v73, v21
	ds_bpermute_b32 v32, v73, v20
	v_lshl_add_u64 v[76:77], s[12:13], 0, v[76:77]
	v_lshl_add_u64 v[76:77], v[76:77], 0, v[80:81]
	s_waitcnt lgkmcnt(0)
	v_pk_add_f32 v[20:21], v[20:21], v[32:33]
	ds_bpermute_b32 v33, v72, v21
	ds_bpermute_b32 v32, v72, v20
	s_waitcnt lgkmcnt(0)
	v_pk_add_f32 v[20:21], v[20:21], v[32:33]
	ds_bpermute_b32 v33, v71, v21
	ds_bpermute_b32 v32, v71, v20
	s_waitcnt lgkmcnt(0)
	v_pk_add_f32 v[20:21], v[20:21], v[32:33]
	ds_bpermute_b32 v33, v67, v21
	ds_bpermute_b32 v32, v67, v20
	s_waitcnt lgkmcnt(0)
	v_pk_add_f32 v[20:21], v[20:21], v[32:33]
	ds_bpermute_b32 v33, v66, v21
	ds_bpermute_b32 v32, v66, v20
	s_waitcnt lgkmcnt(0)
	v_pk_add_f32 v[20:21], v[20:21], v[32:33]
	s_nop 0
	v_pk_fma_f32 v[20:21], v[20:21], s[78:79], v[16:17] op_sel_hi:[1,0,0]
	v_mov_b32_e32 v33, s1
	v_mul_f32_e32 v32, 0x4b800000, v21
	v_cmp_gt_f32_e64 s[6:7], s64, v21
	v_cmp_gt_f32_e32 vcc, s64, v20
	s_nop 0
	v_cndmask_b32_e64 v21, v21, v32, s[6:7]
	v_rsq_f32_e32 v21, v21
	s_nop 0
	v_mul_f32_e32 v32, 0x45800000, v21
	v_cndmask_b32_e64 v21, v21, v32, s[6:7]
	v_mul_f32_e32 v18, v18, v21
	v_mul_f32_e32 v18, v48, v18
	v_bfe_u32 v32, v18, 16, 1
	v_add3_u32 v18, v18, v32, s33
	global_store_short_d16_hi v[76:77], v18, off
	v_mul_f32_e32 v18, v19, v21
	v_mul_f32_e32 v18, v68, v18
	v_bfe_u32 v19, v18, 16, 1
	v_add3_u32 v18, v18, v19, s33
	global_store_short_d16_hi v[76:77], v18, off offset:64
	v_mul_f32_e32 v18, v35, v21
	v_mul_f32_e32 v18, v70, v18
	v_bfe_u32 v19, v18, 16, 1
	v_add3_u32 v18, v18, v19, s33
	global_store_short_d16_hi v[76:77], v18, off offset:128
	v_mul_f32_e32 v18, v34, v21
	v_mul_f32_e32 v18, v69, v18
	v_bfe_u32 v19, v18, 16, 1
	v_add3_u32 v18, v18, v19, s33
	global_store_short_d16_hi v[76:77], v18, off offset:192
	v_mul_f32_e32 v18, 0x4b800000, v20
	v_cndmask_b32_e32 v18, v20, v18, vcc
	v_rsq_f32_e32 v18, v18
	v_or_b32_e32 v32, 10, v64
	v_lshlrev_b64 v[32:33], 12, v[32:33]
	v_lshl_add_u64 v[32:33], s[12:13], 0, v[32:33]
	v_mul_f32_e32 v19, 0x45800000, v18
	v_cndmask_b32_e32 v20, v18, v19, vcc
	v_or_b32_e32 v18, 9, v64
	v_mov_b32_e32 v19, s1
	v_mul_f32_e32 v4, v4, v20
	v_lshlrev_b64 v[18:19], 12, v[18:19]
; DI unsigned f2bf(float f) { unsigned u = __builtin_bit_cast(unsigned, f); return (u + 0x7fffu + ((u >> 16) & 1u)) >> 16; }
; DI float shx(float v, int o, int lane) { return __int_as_float(__builtin_amdgcn_ds_bpermute((lane ^ o) << 2, __float_as_int(v))); }
; DI int crow(int i, int hh) { return (i & 3) + 8 * (i >> 2) + 4 * hh; }
; DI void attn_item(CArgs& a, LAS unsigned char* lds, int l, int b, int h, int qb, int tid_, int wave, int lane_) {
;     ...
;     for (int i = 0; i < 16; ++i) { const float inv = scr[crow(i, hh)]; float s = 0.f;
; #pragma unroll
;         for (int vt = 0; vt < 4; ++vt) { o[vt][i] *= inv; s += o[vt][i] * o[vt][i]; }
;         s += shx(s, 1, lane); s += shx(s, 2, lane); s += shx(s, 4, lane); s += shx(s, 8, lane); s += shx(s, 16, lane);
;         const float rs = rsqrtf(s * (1.f / 128.f) + EPS);
; #pragma unroll
;         for (int vt = 0; vt < 4; ++vt) { const int col = h * 128 + 32 * vt + r; mix[(trow0 + crow(i, hh)) * DM + 1024 + col] = (bf16_t)f2bf(o[vt][i] * rs * a.in[I_MIXG][l * DM + 1024 + col]); } }
	v_mul_f32_e32 v4, v48, v4
	v_lshl_add_u64 v[18:19], s[12:13], 0, v[18:19]
	v_bfe_u32 v21, v4, 16, 1
	v_add3_u32 v4, v4, v21, s33
	v_lshl_add_u64 v[18:19], v[18:19], 0, v[80:81]
	global_store_short_d16_hi v[18:19], v4, off
	v_mul_f32_e32 v4, v5, v20
	v_mul_f32_e32 v4, v68, v4
	v_bfe_u32 v5, v4, 16, 1
	v_mul_f32_e32 v1, v1, v20
	v_add3_u32 v4, v4, v5, s33
	v_mul_f32_e32 v1, v70, v1
	global_store_short_d16_hi v[18:19], v4, off offset:64
	v_bfe_u32 v4, v1, 16, 1
	v_mul_f32_e32 v0, v0, v20
	v_add3_u32 v1, v1, v4, s33
	v_mul_f32_e32 v0, v69, v0
	global_store_short_d16_hi v[18:19], v1, off offset:128
	v_bfe_u32 v1, v0, 16, 1
	v_add3_u32 v0, v0, v1, s33
	global_store_short_d16_hi v[18:19], v0, off offset:192
	v_mov_b32_e32 v0, v6
	v_mov_b32_e32 v1, v22
	v_mov_b32_e32 v18, v54
	v_mov_b32_e32 v19, v38
	v_pk_mul_f32 v[0:1], v[0:1], v[2:3] op_sel_hi:[1,0]
	v_pk_mul_f32 v[18:19], v[18:19], v[2:3] op_sel_hi:[1,0]
	v_mov_b32_e32 v22, v7
	v_mov_b32_e32 v2, v3
	v_pk_mul_f32 v[6:7], v[22:23], v[2:3] op_sel_hi:[1,0]
	v_mov_b32_e32 v38, v55
	v_pk_mul_f32 v[4:5], v[0:1], v[0:1]
	v_pk_mul_f32 v[22:23], v[6:7], v[6:7]
	v_pk_mul_f32 v[2:3], v[38:39], v[2:3] op_sel_hi:[1,0]
	v_pk_mul_f32 v[20:21], v[18:19], v[18:19]
	v_pk_mul_f32 v[34:35], v[2:3], v[2:3]
	v_mov_b32_e32 v36, v22
	v_mov_b32_e32 v37, v4
	v_mov_b32_e32 v4, v23
	v_pk_add_f32 v[4:5], v[36:37], v[4:5]
	v_mov_b32_e32 v22, v35
	v_mov_b32_e32 v23, v21
	v_pk_add_f32 v[4:5], v[22:23], v[4:5]
	v_mov_b32_e32 v35, v20
	v_pk_add_f32 v[4:5], v[34:35], v[4:5]
	ds_bpermute_b32 v21, v73, v5
	ds_bpermute_b32 v20, v73, v4
	v_lshl_add_u64 v[32:33], v[32:33], 0, v[80:81]
	v_or_b32_e32 v22, 16, v64
	v_mov_b32_e32 v23, s1
	v_lshlrev_b64 v[22:23], 12, v[22:23]
	s_waitcnt lgkmcnt(0)
	v_pk_add_f32 v[4:5], v[4:5], v[20:21]
	ds_bpermute_b32 v21, v72, v5
	ds_bpermute_b32 v20, v72, v4
	v_lshl_add_u64 v[22:23], s[12:13], 0, v[22:23]
	v_lshl_add_u64 v[22:23], v[22:23], 0, v[80:81]
	s_waitcnt lgkmcnt(0)
	v_pk_add_f32 v[4:5], v[4:5], v[20:21]
	ds_bpermute_b32 v21, v71, v5
	ds_bpermute_b32 v20, v71, v4
	s_waitcnt lgkmcnt(0)
	v_pk_add_f32 v[4:5], v[4:5], v[20:21]
	ds_bpermute_b32 v21, v67, v5
	ds_bpermute_b32 v20, v67, v4
	s_waitcnt lgkmcnt(0)
	v_pk_add_f32 v[4:5], v[4:5], v[20:21]
	ds_bpermute_b32 v21, v66, v5
	ds_bpermute_b32 v20, v66, v4
	s_waitcnt lgkmcnt(0)
	v_pk_add_f32 v[4:5], v[4:5], v[20:21]
	s_nop 0
	v_pk_fma_f32 v[4:5], v[4:5], s[78:79], v[16:17] op_sel_hi:[1,0,0]
	s_nop 0
	v_mul_f32_e32 v20, 0x4b800000, v5
	v_cmp_gt_f32_e64 s[6:7], s64, v5
	v_cmp_gt_f32_e32 vcc, s64, v4
	s_nop 0
	v_cndmask_b32_e64 v5, v5, v20, s[6:7]
	v_rsq_f32_e32 v5, v5
	s_nop 0
	v_mul_f32_e32 v20, 0x45800000, v5
	v_cndmask_b32_e64 v5, v5, v20, s[6:7]
	v_mul_f32_e32 v0, v0, v5
	v_mul_f32_e32 v0, v48, v0
	v_bfe_u32 v20, v0, 16, 1
	v_add3_u32 v0, v0, v20, s33
	global_store_short_d16_hi v[32:33], v0, off
	v_mul_f32_e32 v0, v1, v5
	v_mul_f32_e32 v0, v68, v0
	v_bfe_u32 v1, v0, 16, 1
	v_add3_u32 v0, v0, v1, s33
	global_store_short_d16_hi v[32:33], v0, off offset:64
	v_mul_f32_e32 v0, v19, v5
	v_mul_f32_e32 v0, v70, v0
	v_bfe_u32 v1, v0, 16, 1
	v_add3_u32 v0, v0, v1, s33
	global_store_short_d16_hi v[32:33], v0, off offset:128
	v_mul_f32_e32 v0, v18, v5
	v_mul_f32_e32 v0, v69, v0
	v_bfe_u32 v1, v0, 16, 1
	v_add3_u32 v0, v0, v1, s33
	global_store_short_d16_hi v[32:33], v0, off offset:192
	v_mul_f32_e32 v0, 0x4b800000, v4
	v_cndmask_b32_e32 v0, v4, v0, vcc
	v_rsq_f32_e32 v0, v0
	v_mov_b32_e32 v18, v56
	v_mov_b32_e32 v19, v40
	v_mov_b32_e32 v40, v57
	v_mul_f32_e32 v1, 0x45800000, v0
	v_cndmask_b32_e32 v4, v0, v1, vcc
	v_or_b32_e32 v0, 11, v64
	v_mov_b32_e32 v1, s1
	v_mul_f32_e32 v5, v6, v4
	v_lshlrev_b64 v[0:1], 12, v[0:1]
	v_mul_f32_e32 v5, v48, v5
	v_lshl_add_u64 v[0:1], s[12:13], 0, v[0:1]
	v_bfe_u32 v6, v5, 16, 1
	v_add3_u32 v5, v5, v6, s33
	v_lshl_add_u64 v[0:1], v[0:1], 0, v[80:81]
	global_store_short_d16_hi v[0:1], v5, off
	v_mul_f32_e32 v5, v7, v4
	v_mul_f32_e32 v5, v68, v5
	v_bfe_u32 v6, v5, 16, 1
	v_mul_f32_e32 v3, v3, v4
	v_add3_u32 v5, v5, v6, s33
	v_mul_f32_e32 v3, v70, v3
	global_store_short_d16_hi v[0:1], v5, off offset:64
	v_bfe_u32 v5, v3, 16, 1
	v_mul_f32_e32 v2, v2, v4
	v_add3_u32 v3, v3, v5, s33
	v_mul_f32_e32 v2, v69, v2
	global_store_short_d16_hi v[0:1], v3, off offset:128
	v_bfe_u32 v3, v2, 16, 1
	v_add3_u32 v2, v2, v3, s33
	global_store_short_d16_hi v[0:1], v2, off offset:192
	ds_read_b128 v[0:3], v74 offset:64
	v_mov_b32_e32 v4, v8
	v_mov_b32_e32 v5, v24
	v_mov_b32_e32 v24, v9
	s_waitcnt lgkmcnt(0)
	v_pk_mul_f32 v[4:5], v[4:5], v[0:1] op_sel_hi:[1,0]
	v_pk_mul_f32 v[8:9], v[24:25], v[0:1] op_sel:[0,1]
	v_pk_mul_f32 v[6:7], v[4:5], v[4:5]
	v_pk_mul_f32 v[18:19], v[18:19], v[0:1] op_sel_hi:[1,0]
	v_pk_mul_f32 v[24:25], v[8:9], v[8:9]
	v_pk_mul_f32 v[0:1], v[40:41], v[0:1] op_sel:[0,1]
	v_pk_mul_f32 v[20:21], v[18:19], v[18:19]
	v_pk_mul_f32 v[32:33], v[0:1], v[0:1]
	v_mov_b32_e32 v34, v24
	v_mov_b32_e32 v35, v6
	v_mov_b32_e32 v6, v25
	v_pk_add_f32 v[6:7], v[34:35], v[6:7]
	v_mov_b32_e32 v24, v33
	v_mov_b32_e32 v25, v21
	v_pk_add_f32 v[6:7], v[24:25], v[6:7]
	v_mov_b32_e32 v33, v20
	v_pk_add_f32 v[6:7], v[32:33], v[6:7]
	ds_bpermute_b32 v21, v73, v7
	ds_bpermute_b32 v20, v73, v6
	s_waitcnt lgkmcnt(0)
	v_pk_add_f32 v[6:7], v[6:7], v[20:21]
	ds_bpermute_b32 v21, v72, v7
	ds_bpermute_b32 v20, v72, v6
	s_waitcnt lgkmcnt(0)
	v_pk_add_f32 v[6:7], v[6:7], v[20:21]
	ds_bpermute_b32 v21, v71, v7
	ds_bpermute_b32 v20, v71, v6
	s_waitcnt lgkmcnt(0)
	v_pk_add_f32 v[6:7], v[6:7], v[20:21]
	ds_bpermute_b32 v21, v67, v7
	ds_bpermute_b32 v20, v67, v6
	s_waitcnt lgkmcnt(0)
	v_pk_add_f32 v[6:7], v[6:7], v[20:21]
	ds_bpermute_b32 v21, v66, v7
	ds_bpermute_b32 v20, v66, v6
	s_waitcnt lgkmcnt(0)
; DI unsigned f2bf(float f) { unsigned u = __builtin_bit_cast(unsigned, f); return (u + 0x7fffu + ((u >> 16) & 1u)) >> 16; }
; DI float shx(float v, int o, int lane) { return __int_as_float(__builtin_amdgcn_ds_bpermute((lane ^ o) << 2, __float_as_int(v))); }
; DI int crow(int i, int hh) { return (i & 3) + 8 * (i >> 2) + 4 * hh; }
; DI void attn_item(CArgs& a, LAS unsigned char* lds, int l, int b, int h, int qb, int tid_, int wave, int lane_) {
;     ...
;     for (int i = 0; i < 16; ++i) { const float inv = scr[crow(i, hh)]; float s = 0.f;
; #pragma unroll
;         for (int vt = 0; vt < 4; ++vt) { o[vt][i] *= inv; s += o[vt][i] * o[vt][i]; }
;         s += shx(s, 1, lane); s += shx(s, 2, lane); s += shx(s, 4, lane); s += shx(s, 8, lane); s += shx(s, 16, lane);
;         const float rs = rsqrtf(s * (1.f / 128.f) + EPS);
; #pragma unroll
;         for (int vt = 0; vt < 4; ++vt) { const int col = h * 128 + 32 * vt + r; mix[(trow0 + crow(i, hh)) * DM + 1024 + col] = (bf16_t)f2bf(o[vt][i] * rs * a.in[I_MIXG][l * DM + 1024 + col]); } }
	v_pk_add_f32 v[6:7], v[6:7], v[20:21]
	s_nop 0
	v_pk_fma_f32 v[6:7], v[6:7], s[78:79], v[16:17] op_sel_hi:[1,0,0]
	s_nop 0
	v_mul_f32_e32 v20, 0x4b800000, v7
	v_cmp_gt_f32_e64 s[6:7], s64, v7
	v_cmp_gt_f32_e32 vcc, s64, v6
	s_nop 0
	v_cndmask_b32_e64 v7, v7, v20, s[6:7]
	v_rsq_f32_e32 v7, v7
	s_nop 0
	v_mul_f32_e32 v20, 0x45800000, v7
	v_cndmask_b32_e64 v7, v7, v20, s[6:7]
	v_mul_f32_e32 v4, v4, v7
	v_mul_f32_e32 v4, v48, v4
	v_bfe_u32 v20, v4, 16, 1
	v_add3_u32 v4, v4, v20, s33
	global_store_short_d16_hi v[22:23], v4, off
	v_mul_f32_e32 v4, v5, v7
	v_mul_f32_e32 v4, v68, v4
	v_bfe_u32 v5, v4, 16, 1
	v_add3_u32 v4, v4, v5, s33
	global_store_short_d16_hi v[22:23], v4, off offset:64
	v_mul_f32_e32 v4, v19, v7
	v_mul_f32_e32 v4, v70, v4
	v_bfe_u32 v5, v4, 16, 1
	v_add3_u32 v4, v4, v5, s33
	global_store_short_d16_hi v[22:23], v4, off offset:128
	v_mul_f32_e32 v4, v18, v7
	v_mul_f32_e32 v4, v69, v4
	v_bfe_u32 v5, v4, 16, 1
	v_add3_u32 v4, v4, v5, s33
	global_store_short_d16_hi v[22:23], v4, off offset:192
	v_mul_f32_e32 v4, 0x4b800000, v6
	v_cndmask_b32_e32 v4, v6, v4, vcc
	v_rsq_f32_e32 v4, v4
	v_or_b32_e32 v18, 18, v64
	v_mov_b32_e32 v19, s1
	v_lshlrev_b64 v[18:19], 12, v[18:19]
	v_mul_f32_e32 v5, 0x45800000, v4
	v_cndmask_b32_e32 v6, v4, v5, vcc
	v_or_b32_e32 v4, 17, v64
	v_mov_b32_e32 v5, s1
	v_mul_f32_e32 v7, v8, v6
	v_lshlrev_b64 v[4:5], 12, v[4:5]
	v_mul_f32_e32 v7, v48, v7
	v_lshl_add_u64 v[4:5], s[12:13], 0, v[4:5]
	v_bfe_u32 v8, v7, 16, 1
	v_add3_u32 v7, v7, v8, s33
	v_lshl_add_u64 v[4:5], v[4:5], 0, v[80:81]
	global_store_short_d16_hi v[4:5], v7, off
	v_mul_f32_e32 v7, v9, v6
	v_mul_f32_e32 v7, v68, v7
	v_bfe_u32 v8, v7, 16, 1
	v_mul_f32_e32 v1, v1, v6
	v_add3_u32 v7, v7, v8, s33
	v_mul_f32_e32 v1, v70, v1
	global_store_short_d16_hi v[4:5], v7, off offset:64
	v_bfe_u32 v7, v1, 16, 1
	v_mul_f32_e32 v0, v0, v6
	v_add3_u32 v1, v1, v7, s33
	v_mul_f32_e32 v0, v69, v0
	global_store_short_d16_hi v[4:5], v1, off offset:128
	v_bfe_u32 v1, v0, 16, 1
	v_add3_u32 v0, v0, v1, s33
	global_store_short_d16_hi v[4:5], v0, off offset:192
	v_mov_b32_e32 v0, v10
	v_mov_b32_e32 v1, v26
	v_mov_b32_e32 v6, v58
	v_mov_b32_e32 v7, v42
	v_pk_mul_f32 v[0:1], v[0:1], v[2:3] op_sel_hi:[1,0]
	v_pk_mul_f32 v[6:7], v[6:7], v[2:3] op_sel_hi:[1,0]
	v_mov_b32_e32 v26, v11
	v_mov_b32_e32 v2, v3
	v_pk_mul_f32 v[10:11], v[26:27], v[2:3] op_sel_hi:[1,0]
	v_mov_b32_e32 v42, v59
	v_pk_mul_f32 v[4:5], v[0:1], v[0:1]
	v_pk_mul_f32 v[20:21], v[10:11], v[10:11]
	v_pk_mul_f32 v[2:3], v[42:43], v[2:3] op_sel_hi:[1,0]
	v_pk_mul_f32 v[8:9], v[6:7], v[6:7]
	v_pk_mul_f32 v[22:23], v[2:3], v[2:3]
	v_mov_b32_e32 v24, v20
	v_mov_b32_e32 v25, v4
	v_mov_b32_e32 v4, v21
	v_pk_add_f32 v[4:5], v[24:25], v[4:5]
	v_mov_b32_e32 v20, v23
	v_mov_b32_e32 v21, v9
	v_pk_add_f32 v[4:5], v[20:21], v[4:5]
	v_mov_b32_e32 v23, v8
	v_pk_add_f32 v[4:5], v[22:23], v[4:5]
	ds_bpermute_b32 v9, v73, v5
	ds_bpermute_b32 v8, v73, v4
	v_lshl_add_u64 v[18:19], s[12:13], 0, v[18:19]
	v_lshl_add_u64 v[18:19], v[18:19], 0, v[80:81]
	s_waitcnt lgkmcnt(0)
	v_pk_add_f32 v[4:5], v[4:5], v[8:9]
	ds_bpermute_b32 v9, v72, v5
	ds_bpermute_b32 v8, v72, v4
	s_waitcnt lgkmcnt(0)
	v_pk_add_f32 v[4:5], v[4:5], v[8:9]
	ds_bpermute_b32 v9, v71, v5
	ds_bpermute_b32 v8, v71, v4
	s_waitcnt lgkmcnt(0)
	v_pk_add_f32 v[4:5], v[4:5], v[8:9]
	ds_bpermute_b32 v9, v67, v5
	ds_bpermute_b32 v8, v67, v4
	s_waitcnt lgkmcnt(0)
	v_pk_add_f32 v[4:5], v[4:5], v[8:9]
	ds_bpermute_b32 v9, v66, v5
	ds_bpermute_b32 v8, v66, v4
	s_waitcnt lgkmcnt(0)
	v_pk_add_f32 v[4:5], v[4:5], v[8:9]
	s_nop 0
	v_pk_fma_f32 v[4:5], v[4:5], s[78:79], v[16:17] op_sel_hi:[1,0,0]
	v_mov_b32_e32 v9, v44
	v_mul_f32_e32 v8, 0x4b800000, v5
	v_cmp_gt_f32_e64 s[6:7], s64, v5
	v_cmp_gt_f32_e32 vcc, s64, v4
	v_mov_b32_e32 v44, v61
	v_cndmask_b32_e64 v5, v5, v8, s[6:7]
	v_rsq_f32_e32 v5, v5
	s_nop 0
	v_mul_f32_e32 v8, 0x45800000, v5
	v_cndmask_b32_e64 v5, v5, v8, s[6:7]
	v_mul_f32_e32 v0, v0, v5
	v_mul_f32_e32 v0, v48, v0
	v_bfe_u32 v8, v0, 16, 1
	v_add3_u32 v0, v0, v8, s33
	global_store_short_d16_hi v[18:19], v0, off
	v_mul_f32_e32 v0, v1, v5
	v_mul_f32_e32 v0, v68, v0
	v_bfe_u32 v1, v0, 16, 1
	v_add3_u32 v0, v0, v1, s33
	global_store_short_d16_hi v[18:19], v0, off offset:64
	v_mul_f32_e32 v0, v7, v5
	v_mul_f32_e32 v0, v70, v0
	v_bfe_u32 v1, v0, 16, 1
	v_add3_u32 v0, v0, v1, s33
	global_store_short_d16_hi v[18:19], v0, off offset:128
	v_mul_f32_e32 v0, v6, v5
	v_mul_f32_e32 v0, v69, v0
	v_bfe_u32 v1, v0, 16, 1
	v_add3_u32 v0, v0, v1, s33
	global_store_short_d16_hi v[18:19], v0, off offset:192
	v_mul_f32_e32 v0, 0x4b800000, v4
	v_cndmask_b32_e32 v0, v4, v0, vcc
	v_rsq_f32_e32 v0, v0
	v_mov_b32_e32 v8, v60
	v_or_b32_e32 v18, 24, v64
	v_mov_b32_e32 v19, s1
	v_mul_f32_e32 v1, 0x45800000, v0
	v_cndmask_b32_e32 v4, v0, v1, vcc
	v_or_b32_e32 v0, 19, v64
	v_mov_b32_e32 v1, s1
	v_mul_f32_e32 v5, v10, v4
	v_lshlrev_b64 v[0:1], 12, v[0:1]
	v_mul_f32_e32 v5, v48, v5
	v_lshl_add_u64 v[0:1], s[12:13], 0, v[0:1]
	v_bfe_u32 v6, v5, 16, 1
	v_add3_u32 v5, v5, v6, s33
	v_lshl_add_u64 v[0:1], v[0:1], 0, v[80:81]
	global_store_short_d16_hi v[0:1], v5, off
	v_mul_f32_e32 v5, v11, v4
	v_mul_f32_e32 v5, v68, v5
	v_bfe_u32 v6, v5, 16, 1
	v_mul_f32_e32 v3, v3, v4
	v_add3_u32 v5, v5, v6, s33
	v_mul_f32_e32 v3, v70, v3
	global_store_short_d16_hi v[0:1], v5, off offset:64
	v_bfe_u32 v5, v3, 16, 1
	v_mul_f32_e32 v2, v2, v4
	v_add3_u32 v3, v3, v5, s33
	v_mul_f32_e32 v2, v69, v2
	global_store_short_d16_hi v[0:1], v3, off offset:128
	v_bfe_u32 v3, v2, 16, 1
	v_add3_u32 v2, v2, v3, s33
	global_store_short_d16_hi v[0:1], v2, off offset:192
	ds_read_b128 v[0:3], v74 offset:96
	v_mov_b32_e32 v4, v12
	v_mov_b32_e32 v5, v28
	v_mov_b32_e32 v28, v13
	v_lshlrev_b64 v[18:19], 12, v[18:19]
	s_waitcnt lgkmcnt(0)
; DI unsigned f2bf(float f) { unsigned u = __builtin_bit_cast(unsigned, f); return (u + 0x7fffu + ((u >> 16) & 1u)) >> 16; }
; DI float shx(float v, int o, int lane) { return __int_as_float(__builtin_amdgcn_ds_bpermute((lane ^ o) << 2, __float_as_int(v))); }
; DI int crow(int i, int hh) { return (i & 3) + 8 * (i >> 2) + 4 * hh; }
; DI void attn_item(CArgs& a, LAS unsigned char* lds, int l, int b, int h, int qb, int tid_, int wave, int lane_) {
;     ...
;     for (int i = 0; i < 16; ++i) { const float inv = scr[crow(i, hh)]; float s = 0.f;
; #pragma unroll
;         for (int vt = 0; vt < 4; ++vt) { o[vt][i] *= inv; s += o[vt][i] * o[vt][i]; }
;         s += shx(s, 1, lane); s += shx(s, 2, lane); s += shx(s, 4, lane); s += shx(s, 8, lane); s += shx(s, 16, lane);
;         const float rs = rsqrtf(s * (1.f / 128.f) + EPS);
; #pragma unroll
;         for (int vt = 0; vt < 4; ++vt) { const int col = h * 128 + 32 * vt + r; mix[(trow0 + crow(i, hh)) * DM + 1024 + col] = (bf16_t)f2bf(o[vt][i] * rs * a.in[I_MIXG][l * DM + 1024 + col]); } }
;     asm volatile("s_waitcnt lgkmcnt(0)" ::: "memory");
	v_pk_mul_f32 v[4:5], v[4:5], v[0:1] op_sel_hi:[1,0]
	v_pk_mul_f32 v[12:13], v[28:29], v[0:1] op_sel:[0,1]
	v_pk_mul_f32 v[6:7], v[4:5], v[4:5]
	v_pk_mul_f32 v[8:9], v[8:9], v[0:1] op_sel_hi:[1,0]
	v_pk_mul_f32 v[20:21], v[12:13], v[12:13]
	v_pk_mul_f32 v[0:1], v[44:45], v[0:1] op_sel:[0,1]
	v_pk_mul_f32 v[10:11], v[8:9], v[8:9]
	v_pk_mul_f32 v[22:23], v[0:1], v[0:1]
	v_mov_b32_e32 v24, v20
	v_mov_b32_e32 v25, v6
	v_mov_b32_e32 v6, v21
	v_pk_add_f32 v[6:7], v[24:25], v[6:7]
	v_mov_b32_e32 v20, v23
	v_mov_b32_e32 v21, v11
	v_pk_add_f32 v[6:7], v[20:21], v[6:7]
	v_mov_b32_e32 v23, v10
	v_pk_add_f32 v[6:7], v[22:23], v[6:7]
	ds_bpermute_b32 v11, v73, v7
	ds_bpermute_b32 v10, v73, v6
	v_lshl_add_u64 v[18:19], s[12:13], 0, v[18:19]
	v_lshl_add_u64 v[18:19], v[18:19], 0, v[80:81]
	s_waitcnt lgkmcnt(0)
	v_pk_add_f32 v[6:7], v[6:7], v[10:11]
	ds_bpermute_b32 v11, v72, v7
	ds_bpermute_b32 v10, v72, v6
	s_waitcnt lgkmcnt(0)
	v_pk_add_f32 v[6:7], v[6:7], v[10:11]
	ds_bpermute_b32 v11, v71, v7
	ds_bpermute_b32 v10, v71, v6
	s_waitcnt lgkmcnt(0)
	v_pk_add_f32 v[6:7], v[6:7], v[10:11]
	ds_bpermute_b32 v11, v67, v7
	ds_bpermute_b32 v10, v67, v6
	s_waitcnt lgkmcnt(0)
	v_pk_add_f32 v[6:7], v[6:7], v[10:11]
	ds_bpermute_b32 v11, v66, v7
	ds_bpermute_b32 v10, v66, v6
	s_waitcnt lgkmcnt(0)
	v_pk_add_f32 v[6:7], v[6:7], v[10:11]
	s_nop 0
	v_pk_fma_f32 v[6:7], v[6:7], s[78:79], v[16:17] op_sel_hi:[1,0,0]
	v_mov_b32_e32 v11, s1
	v_mul_f32_e32 v10, 0x4b800000, v7
	v_cmp_gt_f32_e64 s[6:7], s64, v7
	v_cmp_gt_f32_e32 vcc, s64, v6
	s_nop 0
	v_cndmask_b32_e64 v7, v7, v10, s[6:7]
	v_rsq_f32_e32 v7, v7
	s_nop 0
	v_mul_f32_e32 v10, 0x45800000, v7
	v_cndmask_b32_e64 v7, v7, v10, s[6:7]
	v_mul_f32_e32 v4, v4, v7
	v_mul_f32_e32 v4, v48, v4
	v_bfe_u32 v10, v4, 16, 1
	v_add3_u32 v4, v4, v10, s33
	global_store_short_d16_hi v[18:19], v4, off
	v_mul_f32_e32 v4, v5, v7
	v_mul_f32_e32 v4, v68, v4
	v_bfe_u32 v5, v4, 16, 1
	v_add3_u32 v4, v4, v5, s33
	global_store_short_d16_hi v[18:19], v4, off offset:64
	v_mul_f32_e32 v4, v9, v7
	v_mul_f32_e32 v4, v70, v4
	v_bfe_u32 v5, v4, 16, 1
	v_add3_u32 v4, v4, v5, s33
	global_store_short_d16_hi v[18:19], v4, off offset:128
	v_mul_f32_e32 v4, v8, v7
	v_mul_f32_e32 v4, v69, v4
	v_bfe_u32 v5, v4, 16, 1
	v_add3_u32 v4, v4, v5, s33
	global_store_short_d16_hi v[18:19], v4, off offset:192
	v_mul_f32_e32 v4, 0x4b800000, v6
	v_cndmask_b32_e32 v4, v6, v4, vcc
	v_rsq_f32_e32 v4, v4
	v_or_b32_e32 v10, 26, v64
	v_lshlrev_b64 v[10:11], 12, v[10:11]
	v_lshl_add_u64 v[10:11], s[12:13], 0, v[10:11]
	v_mul_f32_e32 v5, 0x45800000, v4
	v_cndmask_b32_e32 v6, v4, v5, vcc
	v_or_b32_e32 v4, 25, v64
	v_mov_b32_e32 v5, s1
	v_mul_f32_e32 v7, v12, v6
	v_lshlrev_b64 v[4:5], 12, v[4:5]
	v_mul_f32_e32 v7, v48, v7
	v_lshl_add_u64 v[4:5], s[12:13], 0, v[4:5]
	v_bfe_u32 v8, v7, 16, 1
	v_add3_u32 v7, v7, v8, s33
	v_lshl_add_u64 v[4:5], v[4:5], 0, v[80:81]
	global_store_short_d16_hi v[4:5], v7, off
	v_mul_f32_e32 v7, v13, v6
	v_mul_f32_e32 v7, v68, v7
	v_bfe_u32 v8, v7, 16, 1
	v_mul_f32_e32 v1, v1, v6
	v_add3_u32 v7, v7, v8, s33
	v_mul_f32_e32 v1, v70, v1
	global_store_short_d16_hi v[4:5], v7, off offset:64
	v_bfe_u32 v7, v1, 16, 1
	v_mul_f32_e32 v0, v0, v6
	v_add3_u32 v1, v1, v7, s33
	v_mul_f32_e32 v0, v69, v0
	global_store_short_d16_hi v[4:5], v1, off offset:128
	v_bfe_u32 v1, v0, 16, 1
	v_add3_u32 v0, v0, v1, s33
	global_store_short_d16_hi v[4:5], v0, off offset:192
	v_mov_b32_e32 v0, v14
	v_mov_b32_e32 v1, v30
	v_mov_b32_e32 v6, v62
	v_mov_b32_e32 v7, v46
	v_pk_mul_f32 v[0:1], v[0:1], v[2:3] op_sel_hi:[1,0]
	v_pk_mul_f32 v[6:7], v[6:7], v[2:3] op_sel_hi:[1,0]
	v_mov_b32_e32 v30, v15
	v_mov_b32_e32 v2, v3
	v_pk_mul_f32 v[12:13], v[30:31], v[2:3] op_sel_hi:[1,0]
	v_mov_b32_e32 v46, v63
	v_pk_mul_f32 v[4:5], v[0:1], v[0:1]
	v_pk_mul_f32 v[14:15], v[12:13], v[12:13]
	v_pk_mul_f32 v[2:3], v[46:47], v[2:3] op_sel_hi:[1,0]
	v_pk_mul_f32 v[8:9], v[6:7], v[6:7]
	v_pk_mul_f32 v[18:19], v[2:3], v[2:3]
	v_mov_b32_e32 v20, v14
	v_mov_b32_e32 v21, v4
	v_mov_b32_e32 v4, v15
	v_pk_add_f32 v[4:5], v[20:21], v[4:5]
	v_mov_b32_e32 v14, v19
	v_mov_b32_e32 v15, v9
	v_pk_add_f32 v[4:5], v[14:15], v[4:5]
	v_mov_b32_e32 v19, v8
	v_pk_add_f32 v[4:5], v[18:19], v[4:5]
	ds_bpermute_b32 v9, v73, v5
	ds_bpermute_b32 v8, v73, v4
	v_lshl_add_u64 v[10:11], v[10:11], 0, v[80:81]
	v_or_b32_e32 v64, 27, v64
	s_waitcnt lgkmcnt(0)
	v_pk_add_f32 v[4:5], v[4:5], v[8:9]
	ds_bpermute_b32 v9, v72, v5
	ds_bpermute_b32 v8, v72, v4
	s_waitcnt lgkmcnt(0)
	v_pk_add_f32 v[4:5], v[4:5], v[8:9]
	ds_bpermute_b32 v9, v71, v5
	ds_bpermute_b32 v8, v71, v4
	s_waitcnt lgkmcnt(0)
	v_pk_add_f32 v[4:5], v[4:5], v[8:9]
	ds_bpermute_b32 v9, v67, v5
	ds_bpermute_b32 v8, v67, v4
	s_waitcnt lgkmcnt(0)
	v_pk_add_f32 v[4:5], v[4:5], v[8:9]
	ds_bpermute_b32 v9, v66, v5
	ds_bpermute_b32 v8, v66, v4
	s_waitcnt lgkmcnt(0)
	v_pk_add_f32 v[4:5], v[4:5], v[8:9]
	s_nop 0
	v_pk_fma_f32 v[4:5], v[4:5], s[78:79], v[16:17] op_sel_hi:[1,0,0]
	s_nop 0
	v_mul_f32_e32 v8, 0x4b800000, v5
	v_cmp_gt_f32_e64 s[6:7], s64, v5
	v_cmp_gt_f32_e32 vcc, s64, v4
	s_nop 0
	v_cndmask_b32_e64 v5, v5, v8, s[6:7]
	v_rsq_f32_e32 v5, v5
	s_nop 0
	v_mul_f32_e32 v8, 0x45800000, v5
	v_cndmask_b32_e64 v5, v5, v8, s[6:7]
	v_mul_f32_e32 v0, v0, v5
	v_mul_f32_e32 v0, v48, v0
	v_bfe_u32 v8, v0, 16, 1
	v_add3_u32 v0, v0, v8, s33
	global_store_short_d16_hi v[10:11], v0, off
	v_mul_f32_e32 v0, v1, v5
	v_mul_f32_e32 v0, v68, v0
	v_bfe_u32 v1, v0, 16, 1
	v_add3_u32 v0, v0, v1, s33
	global_store_short_d16_hi v[10:11], v0, off offset:64
	v_mul_f32_e32 v0, v7, v5
	v_mul_f32_e32 v0, v70, v0
	v_bfe_u32 v1, v0, 16, 1
	v_add3_u32 v0, v0, v1, s33
	global_store_short_d16_hi v[10:11], v0, off offset:128
	v_mul_f32_e32 v0, v6, v5
	v_mul_f32_e32 v0, v69, v0
	v_bfe_u32 v1, v0, 16, 1
	v_add3_u32 v0, v0, v1, s33
	global_store_short_d16_hi v[10:11], v0, off offset:192
	v_mul_f32_e32 v0, 0x4b800000, v4
	v_cndmask_b32_e32 v0, v4, v0, vcc
	v_rsq_f32_e32 v0, v0
	s_nop 0
	v_mul_f32_e32 v1, 0x45800000, v0
	v_cndmask_b32_e32 v4, v0, v1, vcc
	v_mul_f32_e32 v5, v12, v4
	v_lshlrev_b64 v[0:1], 12, v[64:65]
	v_mul_f32_e32 v5, v48, v5
	v_lshl_add_u64 v[0:1], s[12:13], 0, v[0:1]
	v_bfe_u32 v6, v5, 16, 1
	v_add3_u32 v5, v5, v6, s33
	v_lshl_add_u64 v[0:1], v[0:1], 0, v[80:81]
	global_store_short_d16_hi v[0:1], v5, off
	v_mul_f32_e32 v5, v13, v4
	v_mul_f32_e32 v5, v68, v5
	v_bfe_u32 v6, v5, 16, 1
	v_mul_f32_e32 v3, v3, v4
	v_add3_u32 v5, v5, v6, s33
	v_mul_f32_e32 v3, v70, v3
	global_store_short_d16_hi v[0:1], v5, off offset:64
	v_bfe_u32 v5, v3, 16, 1
	v_mul_f32_e32 v2, v2, v4
	v_add3_u32 v3, v3, v5, s33
	v_mul_f32_e32 v2, v69, v2
	global_store_short_d16_hi v[0:1], v3, off offset:128
	v_bfe_u32 v3, v2, 16, 1
	v_add3_u32 v2, v2, v3, s33
	global_store_short_d16_hi v[0:1], v2, off offset:192
	v_lshlrev_b32_e32 v250, 4, v187
	v_add_u32_e32 v250, 0x18000, v250
	ds_read_b128 v[82:85], v250
	ds_read_b128 v[86:89], v250 offset:8192
	ds_read_b128 v[90:93], v250 offset:16384
	ds_read_b128 v[94:97], v250 offset:24576
	s_waitcnt lgkmcnt(0)
	s_cbranch_scc1 .LBB0_337
; #define LAS __attribute__((address_space(3)))
; DI void unpack8(const u32x4 w, float (&f)[8]) { f[0] = bflo(w.x); f[1] = bfhi(w.x); f[2] = bflo(w.y); f[3] = bfhi(w.y); f[4] = bflo(w.z); f[5] = bfhi(w.z); f[6] = bflo(w.w); f[7] = bfhi(w.w); }
; DI u32x4 pack8f(const float (&f)[8]) { u32x4 w; w.x = pk2(f[0], f[1]); w.y = pk2(f[2], f[3]); w.z = pk2(f[4], f[5]); w.w = pk2(f[6], f[7]); return w; }
; DI void attn_item(CArgs& a, LAS unsigned char* lds, int l, int b, int h, int qb, int tid_, int wave, int lane_) {
;     int tid = tid_; asm volatile("" : "+v"(tid)); const int lane = tid & 63;
;     LAS float* scr = (LAS float*)(lds + AT_SCR) + wave * 64;
;     const int r = lane & 31, hh = lane >> 5;
;     const int qloc = qb * 256 + wave * 32 + r; const size_t tq = (size_t)b * S_ + qloc;
;     AttnOff F;
; #pragma unroll
;     for (int i = 0; i < 2; ++i) { const int ck = tid + 512 * i, row = ck >> 4, cc = ck & 15; F.gk[i] = (unsigned)(row * 512 + 8 * cc) * 2u; }
;     { const int row = tid >> 3, cc = tid & 7; F.gr = (unsigned)(row * 64 + 8 * cc) * 2u; }
; #pragma unroll
;     for (int i = 0; i < 2; ++i) { const int cv = tid + 512 * i, v = cv >> 3, cc = cv & 7; F.gv[i] = (unsigned)(v * T_ + 8 * cc) * 2u; }
;     bf16x8 qf[12];
;     { const bf16_t* qp = (const bf16_t*)(a.ws + B_QB) + tq * 768 + h * 192; const float sc = 0.07216878364870322f * 1.4426950408889634f;
; #pragma unroll
;       for (int ks = 0; ks < 8; ++ks) { float f[8]; unpack8(*(const u32x4*)(qp + 16 * ks + 8 * hh), f);
; #pragma unroll
;           for (int e = 0; e < 8; ++e) f[e] *= sc;
;           qf[ks] = __builtin_bit_cast(bf16x8, pack8f(f)); }
.LBB0_295:
	v_lshlrev_b32_e32 v250, 4, v187
	v_add_u32_e32 v250, 0x18000, v250
	ds_write_b128 v250, v[82:85]
	ds_write_b128 v250, v[86:89] offset:8192
	ds_write_b128 v250, v[90:93] offset:16384
	ds_write_b128 v250, v[94:97] offset:24576
	s_and_b32 s47, s42, 31
	s_and_b32 s1, s41, 31
	v_mov_b32_e32 v77, v187
	s_lshl_b32 s49, s47, 8
	s_lshl_b32 s50, s1, 8
	s_add_i32 s1, s49, s26
	v_and_b32_e32 v169, 31, v77
	v_lshlrev_b32_e32 v78, 3, v77
	v_or_b32_e32 v174, s1, v169
	v_lshlrev_b32_e32 v0, 5, v77
	v_and_b32_e32 v188, 0x78, v78
	s_mov_b32 s1, 0x7ffffe00
	v_and_or_b32 v1, v0, s1, v188
	v_add_u32_e32 v0, 0x4000, v0
	v_and_or_b32 v0, v0, s1, v188
	s_ashr_i32 s2, s42, 7
	v_lshlrev_b32_e32 v66, 1, v0
	v_lshlrev_b32_e32 v0, 12, v77
	v_and_b32_e32 v79, 56, v78
	s_mov_b32 s1, 0x7fff8000
	s_ashr_i32 s3, s2, 31
	v_lshlrev_b32_e32 v64, 1, v1
	v_and_or_b32 v1, v0, s1, v79
	v_add_u32_e32 v0, 0x200000, v0
	v_ashrrev_i32_e32 v175, 31, v174
	s_lshl_b64 s[14:15], s[2:3], 14
	v_and_or_b32 v0, v0, s1, v79
	s_bfe_u32 s0, s42, 0x20005
	v_lshlrev_b32_e32 v70, 1, v1
	v_lshlrev_b32_e32 v72, 1, v0
	v_lshl_add_u64 v[0:1], s[14:15], 0, v[174:175]
	v_mov_b64_e32 v[2:3], s[10:11]
	v_mad_u64_u32 v[2:3], s[4:5], v0, s65, v[2:3]
	s_mul_i32 s48, s0, 0xc0
	v_bfe_u32 v76, v77, 5, 1
	v_mad_i32_i24 v3, v1, s65, v3
	s_lshl_b32 s36, s48, 1
	v_lshl_add_u64 v[2:3], v[2:3], 0, s[36:37]
	v_lshlrev_b32_e32 v80, 4, v76
	v_lshl_add_u64 v[4:5], v[2:3], 0, v[80:81]
	global_load_dwordx4 v[6:9], v[4:5], off
	s_mov_b32 s6, 0x3dd53b94
	v_lshlrev_b64 v[0:1], 8, v[0:1]
	s_mov_b32 s1, 0x200000
	s_mov_b64 s[4:5], 0x200000
	s_lshl_b32 s51, s47, 2
	s_lshl_b32 s22, s0, 23
	s_lshl_b32 s38, s0, 8
	s_addk_i32 s50, 0x100
	s_add_i32 s54, s51, 4
	s_lshl_b32 s43, s0, 7
	v_mov_b32_e32 v36, v81
	v_mov_b32_e32 v37, v81
	v_mov_b32_e32 v38, v81
	v_mov_b32_e32 v39, v81
	v_mov_b32_e32 v40, v81
	v_mov_b32_e32 v41, v81
	v_mov_b32_e32 v42, v81
	v_mov_b32_e32 v43, v81
	v_mov_b32_e32 v44, v81
	v_mov_b32_e32 v45, v81
	v_mov_b32_e32 v46, v81
	v_mov_b32_e32 v47, v81
	v_mov_b32_e32 v48, v81
	v_mov_b32_e32 v49, v81
	v_mov_b32_e32 v50, v81
	v_mov_b32_e32 v51, v81
	v_mov_b32_e32 v52, v81
	v_mov_b32_e32 v53, v81
	v_mov_b32_e32 v54, v81
	v_mov_b32_e32 v55, v81
	v_mov_b32_e32 v56, v81
	v_mov_b32_e32 v57, v81
	v_mov_b32_e32 v58, v81
	v_mov_b32_e32 v59, v81
	v_mov_b32_e32 v60, v81
	v_mov_b32_e32 v61, v81
	v_mov_b32_e32 v62, v81
	v_mov_b32_e32 v63, v81
	v_lshlrev_b32_e32 v68, 4, v77
	v_lshrrev_b32_e32 v175, 4, v77
	s_movk_i32 s23, 0x110
	v_lshl_add_u32 v176, v188, 1, 0
	v_mul_lo_u32 v175, v175, s23
	v_add_u32_e32 v177, v176, v175
	v_and_b32_e32 v74, 63, v77
	v_and_b32_e32 v78, 48, v78
	s_movk_i32 s55, 0x90
	v_lshlrev_b32_e32 v192, 1, v78
	s_mov_b32 s57, s15
	v_lshlrev_b32_e32 v191, 1, v79
	v_lshlrev_b32_e32 v75, 3, v76
	v_mov_b32_e32 v65, v81
	v_mov_b32_e32 v67, v81
	v_mov_b32_e32 v69, v81
	v_mov_b32_e32 v71, v81
	v_mov_b32_e32 v73, v81
	v_lshlrev_b32_e32 v196, 2, v74
	s_mov_b32 s36, 0
	v_lshlrev_b32_e32 v195, 2, v76
	v_xor_b32_e32 v198, 0x80, v196
	v_lshl_add_u32 v197, v169, 2, s27
	v_mul_u32_u24_e32 v199, 0x90, v169
	v_mul_u32_u24_e32 v200, 0x110, v169
	v_mad_u32_u24 v201, v169, s55, v222
	v_mov_b32_e32 v203, 0
	v_mov_b32_e32 v204, 0xff800000
	v_lshlrev_b32_e32 v202, 1, v75
	s_waitcnt vmcnt(0)
	v_lshlrev_b32_e32 v2, 16, v6
	v_and_b32_e32 v3, 0xffff0000, v6
	v_lshlrev_b32_e32 v6, 16, v7
	v_and_b32_e32 v7, 0xffff0000, v7
	v_lshlrev_b32_e32 v10, 16, v8
	v_and_b32_e32 v11, 0xffff0000, v8
	v_lshlrev_b32_e32 v8, 16, v9
	v_and_b32_e32 v9, 0xffff0000, v9
	v_pk_mul_f32 v[6:7], v[6:7], s[6:7] op_sel_hi:[1,0]
	v_pk_mul_f32 v[8:9], v[8:9], s[6:7] op_sel_hi:[1,0]
	v_cvt_pk_bf16_f32 v99, v6, v7
	v_cvt_pk_bf16_f32 v101, v8, v9
	global_load_dwordx4 v[6:9], v[4:5], off offset:32
	v_pk_mul_f32 v[2:3], v[2:3], s[6:7] op_sel_hi:[1,0]
	v_pk_mul_f32 v[10:11], v[10:11], s[6:7] op_sel_hi:[1,0]
	v_cvt_pk_bf16_f32 v98, v2, v3
	v_cvt_pk_bf16_f32 v100, v10, v11
	s_waitcnt vmcnt(0)
	v_lshlrev_b32_e32 v2, 16, v6
	v_and_b32_e32 v3, 0xffff0000, v6
	v_lshlrev_b32_e32 v6, 16, v7
	v_and_b32_e32 v7, 0xffff0000, v7
	v_lshlrev_b32_e32 v10, 16, v8
	v_and_b32_e32 v11, 0xffff0000, v8
	v_lshlrev_b32_e32 v8, 16, v9
	v_and_b32_e32 v9, 0xffff0000, v9
	v_pk_mul_f32 v[6:7], v[6:7], s[6:7] op_sel_hi:[1,0]
	v_pk_mul_f32 v[8:9], v[8:9], s[6:7] op_sel_hi:[1,0]
	v_cvt_pk_bf16_f32 v103, v6, v7
	v_cvt_pk_bf16_f32 v105, v8, v9
	global_load_dwordx4 v[6:9], v[4:5], off offset:64
	v_pk_mul_f32 v[2:3], v[2:3], s[6:7] op_sel_hi:[1,0]
	v_pk_mul_f32 v[10:11], v[10:11], s[6:7] op_sel_hi:[1,0]
	v_cvt_pk_bf16_f32 v102, v2, v3
	v_cvt_pk_bf16_f32 v104, v10, v11
	s_waitcnt vmcnt(0)
	v_lshlrev_b32_e32 v2, 16, v6
	v_and_b32_e32 v3, 0xffff0000, v6
	v_lshlrev_b32_e32 v6, 16, v7
	v_and_b32_e32 v7, 0xffff0000, v7
	v_lshlrev_b32_e32 v10, 16, v8
	v_and_b32_e32 v11, 0xffff0000, v8
	v_lshlrev_b32_e32 v8, 16, v9
	v_and_b32_e32 v9, 0xffff0000, v9
	v_pk_mul_f32 v[6:7], v[6:7], s[6:7] op_sel_hi:[1,0]
	v_pk_mul_f32 v[8:9], v[8:9], s[6:7] op_sel_hi:[1,0]
	v_cvt_pk_bf16_f32 v107, v6, v7
	v_cvt_pk_bf16_f32 v109, v8, v9
	global_load_dwordx4 v[6:9], v[4:5], off offset:96
	v_pk_mul_f32 v[2:3], v[2:3], s[6:7] op_sel_hi:[1,0]
	v_pk_mul_f32 v[10:11], v[10:11], s[6:7] op_sel_hi:[1,0]
	v_cvt_pk_bf16_f32 v106, v2, v3
	v_cvt_pk_bf16_f32 v108, v10, v11
	s_waitcnt vmcnt(0)
	v_lshlrev_b32_e32 v2, 16, v6
	v_and_b32_e32 v3, 0xffff0000, v6
	v_lshlrev_b32_e32 v6, 16, v7
	v_and_b32_e32 v7, 0xffff0000, v7
	v_lshlrev_b32_e32 v10, 16, v8
	v_and_b32_e32 v11, 0xffff0000, v8
	v_lshlrev_b32_e32 v8, 16, v9
	v_and_b32_e32 v9, 0xffff0000, v9
	v_pk_mul_f32 v[6:7], v[6:7], s[6:7] op_sel_hi:[1,0]
	v_pk_mul_f32 v[8:9], v[8:9], s[6:7] op_sel_hi:[1,0]
	v_cvt_pk_bf16_f32 v111, v6, v7
	v_cvt_pk_bf16_f32 v113, v8, v9
	global_load_dwordx4 v[6:9], v[4:5], off offset:128
	v_pk_mul_f32 v[2:3], v[2:3], s[6:7] op_sel_hi:[1,0]
	v_pk_mul_f32 v[10:11], v[10:11], s[6:7] op_sel_hi:[1,0]
	v_cvt_pk_bf16_f32 v110, v2, v3
	v_cvt_pk_bf16_f32 v112, v10, v11
	s_waitcnt vmcnt(0)
; DI void unpack8(const u32x4 w, float (&f)[8]) { f[0] = bflo(w.x); f[1] = bfhi(w.x); f[2] = bflo(w.y); f[3] = bfhi(w.y); f[4] = bflo(w.z); f[5] = bfhi(w.z); f[6] = bflo(w.w); f[7] = bfhi(w.w); }
; DI u32x4 pack8f(const float (&f)[8]) { u32x4 w; w.x = pk2(f[0], f[1]); w.y = pk2(f[2], f[3]); w.z = pk2(f[4], f[5]); w.w = pk2(f[6], f[7]); return w; }
; DI void attn_item(CArgs& a, LAS unsigned char* lds, int l, int b, int h, int qb, int tid_, int wave, int lane_) {
;     ...
;       for (int ks = 0; ks < 8; ++ks) { float f[8]; unpack8(*(const u32x4*)(qp + 16 * ks + 8 * hh), f);
; #pragma unroll
;           for (int e = 0; e < 8; ++e) f[e] *= sc;
;           qf[ks] = __builtin_bit_cast(bf16x8, pack8f(f)); }
; #pragma unroll
;       for (int ks = 8; ks < 10; ++ks) { float x1[8], x2[8], o1[8], o2[8]; unpack8(*(const u32x4*)(qp + 16 * ks + 8 * hh), x1); unpack8(*(const u32x4*)(qp + 16 * (ks + 2) + 8 * hh), x2);
;           const f32x2* cs = (const f32x2*)(a.ws + WS_ROPE) + tq * 32 + 16 * (ks - 8) + 8 * hh;
; #pragma unroll
;           for (int e = 0; e < 8; ++e) { const f32x2 t = cs[e]; o1[e] = (x1[e] * t.x - x2[e] * t.y) * sc; o2[e] = (x1[e] * t.y + x2[e] * t.x) * sc; }
;           qf[ks] = __builtin_bit_cast(bf16x8, pack8f(o1)); qf[ks + 2] = __builtin_bit_cast(bf16x8, pack8f(o2)); } }
	v_lshlrev_b32_e32 v2, 16, v6
	v_and_b32_e32 v3, 0xffff0000, v6
	v_lshlrev_b32_e32 v6, 16, v7
	v_and_b32_e32 v7, 0xffff0000, v7
	v_lshlrev_b32_e32 v10, 16, v8
	v_and_b32_e32 v11, 0xffff0000, v8
	v_lshlrev_b32_e32 v8, 16, v9
	v_and_b32_e32 v9, 0xffff0000, v9
	v_pk_mul_f32 v[6:7], v[6:7], s[6:7] op_sel_hi:[1,0]
	v_pk_mul_f32 v[8:9], v[8:9], s[6:7] op_sel_hi:[1,0]
	v_cvt_pk_bf16_f32 v115, v6, v7
	v_cvt_pk_bf16_f32 v117, v8, v9
	global_load_dwordx4 v[6:9], v[4:5], off offset:160
	v_pk_mul_f32 v[2:3], v[2:3], s[6:7] op_sel_hi:[1,0]
	v_pk_mul_f32 v[10:11], v[10:11], s[6:7] op_sel_hi:[1,0]
	v_cvt_pk_bf16_f32 v114, v2, v3
	v_cvt_pk_bf16_f32 v116, v10, v11
	s_waitcnt vmcnt(0)
	v_lshlrev_b32_e32 v2, 16, v6
	v_and_b32_e32 v3, 0xffff0000, v6
	v_lshlrev_b32_e32 v6, 16, v7
	v_and_b32_e32 v7, 0xffff0000, v7
	v_lshlrev_b32_e32 v10, 16, v8
	v_and_b32_e32 v11, 0xffff0000, v8
	v_lshlrev_b32_e32 v8, 16, v9
	v_and_b32_e32 v9, 0xffff0000, v9
	v_pk_mul_f32 v[6:7], v[6:7], s[6:7] op_sel_hi:[1,0]
	v_pk_mul_f32 v[8:9], v[8:9], s[6:7] op_sel_hi:[1,0]
	v_cvt_pk_bf16_f32 v119, v6, v7
	v_cvt_pk_bf16_f32 v121, v8, v9
	global_load_dwordx4 v[6:9], v[4:5], off offset:192
	v_pk_mul_f32 v[2:3], v[2:3], s[6:7] op_sel_hi:[1,0]
	v_pk_mul_f32 v[10:11], v[10:11], s[6:7] op_sel_hi:[1,0]
	v_cvt_pk_bf16_f32 v118, v2, v3
	v_cvt_pk_bf16_f32 v120, v10, v11
	s_waitcnt vmcnt(0)
	v_lshlrev_b32_e32 v2, 16, v6
	v_and_b32_e32 v3, 0xffff0000, v6
	v_lshlrev_b32_e32 v6, 16, v7
	v_and_b32_e32 v7, 0xffff0000, v7
	v_lshlrev_b32_e32 v10, 16, v8
	v_and_b32_e32 v11, 0xffff0000, v8
	v_lshlrev_b32_e32 v8, 16, v9
	v_and_b32_e32 v9, 0xffff0000, v9
	v_pk_mul_f32 v[6:7], v[6:7], s[6:7] op_sel_hi:[1,0]
	v_pk_mul_f32 v[8:9], v[8:9], s[6:7] op_sel_hi:[1,0]
	v_cvt_pk_bf16_f32 v123, v6, v7
	v_cvt_pk_bf16_f32 v125, v8, v9
	global_load_dwordx4 v[6:9], v[4:5], off offset:224
	v_pk_mul_f32 v[2:3], v[2:3], s[6:7] op_sel_hi:[1,0]
	v_pk_mul_f32 v[10:11], v[10:11], s[6:7] op_sel_hi:[1,0]
	v_cvt_pk_bf16_f32 v122, v2, v3
	v_cvt_pk_bf16_f32 v124, v10, v11
	s_waitcnt vmcnt(0)
	v_lshlrev_b32_e32 v2, 16, v6
	v_and_b32_e32 v3, 0xffff0000, v6
	v_lshlrev_b32_e32 v6, 16, v7
	v_and_b32_e32 v7, 0xffff0000, v7
	v_lshlrev_b32_e32 v10, 16, v8
	v_and_b32_e32 v11, 0xffff0000, v8
	v_lshlrev_b32_e32 v8, 16, v9
	v_and_b32_e32 v9, 0xffff0000, v9
	v_pk_mul_f32 v[6:7], v[6:7], s[6:7] op_sel_hi:[1,0]
	v_pk_mul_f32 v[8:9], v[8:9], s[6:7] op_sel_hi:[1,0]
	v_pk_mul_f32 v[10:11], v[10:11], s[6:7] op_sel_hi:[1,0]
	v_cvt_pk_bf16_f32 v127, v6, v7
	v_cvt_pk_bf16_f32 v129, v8, v9
	v_lshl_add_u64 v[6:7], s[44:45], 0, v[0:1]
	v_lshlrev_b32_e32 v8, 6, v76
	v_mov_b32_e32 v9, v81
	v_pk_mul_f32 v[2:3], v[2:3], s[6:7] op_sel_hi:[1,0]
	v_cvt_pk_bf16_f32 v128, v10, v11
	v_lshl_add_u64 v[10:11], v[6:7], 0, v[8:9]
	v_cvt_pk_bf16_f32 v126, v2, v3
	global_load_dwordx4 v[0:3], v[4:5], off offset:256
	global_load_dwordx4 v[12:15], v[4:5], off offset:320
	v_add_co_u32_e32 v8, vcc, s1, v10
	v_lshl_add_u64 v[6:7], v[10:11], 0, s[4:5]
	s_nop 0
	v_addc_co_u32_e32 v9, vcc, 0, v11, vcc
	global_load_dwordx4 v[16:19], v[8:9], off
	global_load_dwordx4 v[20:23], v[6:7], off offset:48
	global_load_dwordx4 v[24:27], v[6:7], off offset:32
	global_load_dwordx4 v[28:31], v[6:7], off offset:16
	s_mov_b64 s[4:5], 0x200080
	s_lshl_b64 s[0:1], s[2:3], 24
	s_waitcnt vmcnt(5)
	v_lshlrev_b32_e32 v6, 16, v0
	s_waitcnt vmcnt(4)
	v_lshlrev_b32_e32 v32, 16, v12
	v_and_b32_e32 v33, 0xffff0000, v12
	v_and_b32_e32 v7, 0xffff0000, v0
	s_waitcnt vmcnt(3)
	v_mov_b32_e32 v34, v17
	v_mov_b32_e32 v35, v19
	v_mov_b32_e32 v17, v18
	v_pk_mul_f32 v[18:19], v[16:17], v[32:33]
	v_pk_mul_f32 v[32:33], v[34:35], v[32:33]
	v_pk_fma_f32 v[18:19], v[34:35], v[6:7], v[18:19]
	v_pk_fma_f32 v[6:7], v[16:17], v[6:7], v[32:33] neg_lo:[0,0,1] neg_hi:[0,0,1]
	v_lshlrev_b32_e32 v12, 16, v13
	v_and_b32_e32 v13, 0xffff0000, v13
	s_waitcnt vmcnt(0)
	v_mov_b32_e32 v16, v29
	v_mov_b32_e32 v17, v31
	v_mov_b32_e32 v29, v30
	v_lshlrev_b32_e32 v0, 16, v1
	v_and_b32_e32 v1, 0xffff0000, v1
	v_pk_mul_f32 v[30:31], v[28:29], v[12:13]
	v_pk_mul_f32 v[12:13], v[16:17], v[12:13]
	v_pk_fma_f32 v[30:31], v[16:17], v[0:1], v[30:31]
	v_pk_fma_f32 v[0:1], v[28:29], v[0:1], v[12:13] neg_lo:[0,0,1] neg_hi:[0,0,1]
	v_lshlrev_b32_e32 v16, 16, v14
	v_and_b32_e32 v17, 0xffff0000, v14
	v_mov_b32_e32 v28, v25
	v_mov_b32_e32 v29, v27
	v_mov_b32_e32 v25, v26
	v_lshlrev_b32_e32 v12, 16, v2
	v_and_b32_e32 v13, 0xffff0000, v2
	v_pk_mul_f32 v[26:27], v[24:25], v[16:17]
	v_pk_mul_f32 v[16:17], v[28:29], v[16:17]
	v_pk_fma_f32 v[26:27], v[28:29], v[12:13], v[26:27]
	v_pk_fma_f32 v[12:13], v[24:25], v[12:13], v[16:17] neg_lo:[0,0,1] neg_hi:[0,0,1]
	v_lshlrev_b32_e32 v14, 16, v15
	v_and_b32_e32 v15, 0xffff0000, v15
	v_mov_b32_e32 v16, v21
	v_mov_b32_e32 v17, v23
	v_mov_b32_e32 v21, v22
	v_lshlrev_b32_e32 v2, 16, v3
	v_and_b32_e32 v3, 0xffff0000, v3
	v_pk_mul_f32 v[22:23], v[20:21], v[14:15]
	v_pk_mul_f32 v[14:15], v[16:17], v[14:15]
	v_pk_fma_f32 v[22:23], v[16:17], v[2:3], v[22:23]
	v_pk_fma_f32 v[2:3], v[20:21], v[2:3], v[14:15] neg_lo:[0,0,1] neg_hi:[0,0,1]
	v_pk_mul_f32 v[6:7], v[6:7], s[6:7] op_sel_hi:[1,0]
	v_pk_mul_f32 v[0:1], v[0:1], s[6:7] op_sel_hi:[1,0]
	v_pk_mul_f32 v[2:3], v[2:3], s[6:7] op_sel_hi:[1,0]
	v_cvt_pk_bf16_f32 v130, v6, v7
	v_cvt_pk_bf16_f32 v131, v0, v1
	v_cvt_pk_bf16_f32 v133, v2, v3
	global_load_dwordx4 v[0:3], v[4:5], off offset:288
	s_nop 0
	global_load_dwordx4 v[4:7], v[4:5], off offset:352
	v_pk_mul_f32 v[18:19], v[18:19], s[6:7] op_sel_hi:[1,0]
	v_pk_mul_f32 v[12:13], v[12:13], s[6:7] op_sel_hi:[1,0]
	v_pk_mul_f32 v[22:23], v[22:23], s[6:7] op_sel_hi:[1,0]
	v_lshl_add_u64 v[20:21], v[10:11], 0, s[4:5]
	v_cvt_pk_bf16_f32 v132, v12, v13
	v_cvt_pk_bf16_f32 v134, v18, v19
	v_cvt_pk_bf16_f32 v137, v22, v23
	global_load_dwordx4 v[16:19], v[8:9], off offset:128
	s_nop 0
	global_load_dwordx4 v[8:11], v[20:21], off offset:48
	global_load_dwordx4 v[12:15], v[20:21], off offset:32
	s_nop 0
	global_load_dwordx4 v[20:23], v[20:21], off offset:16
	v_pk_mul_f32 v[26:27], v[26:27], s[6:7] op_sel_hi:[1,0]
	s_add_u32 s4, s28, s0
	v_cvt_pk_bf16_f32 v136, v26, v27
	s_addc_u32 s5, s29, s1
	v_pk_mul_f32 v[30:31], v[30:31], s[6:7] op_sel_hi:[1,0]
	s_add_u32 s18, s4, s38
	v_cvt_pk_bf16_f32 v135, v30, v31
	v_mov_b32_e32 v30, v81
	v_mov_b32_e32 v31, v81
	v_mov_b32_e32 v32, v81
	v_mov_b32_e32 v33, v81
	v_mov_b32_e32 v34, v81
	v_mov_b32_e32 v35, v81
	s_addc_u32 s19, s5, 0
	s_lshl_b64 s[4:5], s[2:3], 21
	s_add_u32 s16, s30, s4
	s_addc_u32 s17, s31, s5
	s_lshl_b64 s[20:21], s[2:3], 15
	s_waitcnt vmcnt(5)
; DI void unpack8(const u32x4 w, float (&f)[8]) { f[0] = bflo(w.x); f[1] = bfhi(w.x); f[2] = bflo(w.y); f[3] = bfhi(w.y); f[4] = bflo(w.z); f[5] = bfhi(w.z); f[6] = bflo(w.w); f[7] = bfhi(w.w); }
; DI u32x4 pack8f(const float (&f)[8]) { u32x4 w; w.x = pk2(f[0], f[1]); w.y = pk2(f[2], f[3]); w.z = pk2(f[4], f[5]); w.w = pk2(f[6], f[7]); return w; }
; DI void attn_item(CArgs& a, LAS unsigned char* lds, int l, int b, int h, int qb, int tid_, int wave, int lane_) {
;     ...
;       for (int ks = 8; ks < 10; ++ks) { float x1[8], x2[8], o1[8], o2[8]; unpack8(*(const u32x4*)(qp + 16 * ks + 8 * hh), x1); unpack8(*(const u32x4*)(qp + 16 * (ks + 2) + 8 * hh), x2);
;           const f32x2* cs = (const f32x2*)(a.ws + WS_ROPE) + tq * 32 + 16 * (ks - 8) + 8 * hh;
; #pragma unroll
;           for (int e = 0; e < 8; ++e) { const f32x2 t = cs[e]; o1[e] = (x1[e] * t.x - x2[e] * t.y) * sc; o2[e] = (x1[e] * t.y + x2[e] * t.x) * sc; }
;           qf[ks] = __builtin_bit_cast(bf16x8, pack8f(o1)); qf[ks + 2] = __builtin_bit_cast(bf16x8, pack8f(o2)); } }
;     const int NT = 4 * qb + 4;
;     float m_run = -INFINITY, l_run = 0.f; f32x16 o[4]; o[0] = zero16(); o[1] = zero16(); o[2] = zero16(); o[3] = zero16();
;     u32x4 kr[3], vr[2];
;     attn_load(a, b, h, 0, F, kr, vr);
;     attn_store(lds, tid, kr, vr);
;     attn_load(a, b, h, 1, F, kr, vr);
;     __syncthreads();
	v_lshlrev_b32_e32 v24, 16, v0
	s_waitcnt vmcnt(4)
	v_lshlrev_b32_e32 v26, 16, v4
	v_and_b32_e32 v27, 0xffff0000, v4
	v_and_b32_e32 v25, 0xffff0000, v0
	v_lshlrev_b32_e32 v4, 16, v5
	v_and_b32_e32 v5, 0xffff0000, v5
	s_waitcnt vmcnt(3)
	v_mov_b32_e32 v28, v17
	v_mov_b32_e32 v29, v19
	v_mov_b32_e32 v17, v18
	v_pk_mul_f32 v[18:19], v[16:17], v[26:27]
	v_pk_mul_f32 v[26:27], v[28:29], v[26:27]
	v_pk_fma_f32 v[18:19], v[28:29], v[24:25], v[18:19]
	v_pk_fma_f32 v[16:17], v[16:17], v[24:25], v[26:27] neg_lo:[0,0,1] neg_hi:[0,0,1]
	s_waitcnt vmcnt(0)
	v_mov_b32_e32 v24, v21
	v_mov_b32_e32 v25, v23
	v_mov_b32_e32 v21, v22
	v_lshlrev_b32_e32 v0, 16, v1
	v_and_b32_e32 v1, 0xffff0000, v1
	v_pk_mul_f32 v[22:23], v[20:21], v[4:5]
	v_pk_mul_f32 v[4:5], v[24:25], v[4:5]
	v_pk_fma_f32 v[22:23], v[24:25], v[0:1], v[22:23]
	v_pk_fma_f32 v[0:1], v[20:21], v[0:1], v[4:5] neg_lo:[0,0,1] neg_hi:[0,0,1]
	v_lshlrev_b32_e32 v20, 16, v6
	v_and_b32_e32 v21, 0xffff0000, v6
	v_mov_b32_e32 v24, v13
	v_mov_b32_e32 v25, v15
	v_mov_b32_e32 v13, v14
	v_lshlrev_b32_e32 v4, 16, v2
	v_and_b32_e32 v5, 0xffff0000, v2
	v_pk_mul_f32 v[14:15], v[12:13], v[20:21]
	v_pk_mul_f32 v[20:21], v[24:25], v[20:21]
	v_pk_fma_f32 v[14:15], v[24:25], v[4:5], v[14:15]
	v_pk_fma_f32 v[4:5], v[12:13], v[4:5], v[20:21] neg_lo:[0,0,1] neg_hi:[0,0,1]
	v_lshlrev_b32_e32 v6, 16, v7
	v_and_b32_e32 v7, 0xffff0000, v7
	v_mov_b32_e32 v12, v9
	v_mov_b32_e32 v13, v11
	v_mov_b32_e32 v9, v10
	v_lshlrev_b32_e32 v2, 16, v3
	v_and_b32_e32 v3, 0xffff0000, v3
	v_pk_mul_f32 v[10:11], v[8:9], v[6:7]
	v_pk_mul_f32 v[6:7], v[12:13], v[6:7]
	v_pk_fma_f32 v[10:11], v[12:13], v[2:3], v[10:11]
	v_pk_fma_f32 v[2:3], v[8:9], v[2:3], v[6:7] neg_lo:[0,0,1] neg_hi:[0,0,1]
	v_pk_mul_f32 v[18:19], v[18:19], s[6:7] op_sel_hi:[1,0]
	v_pk_mul_f32 v[16:17], v[16:17], s[6:7] op_sel_hi:[1,0]
	v_pk_mul_f32 v[22:23], v[22:23], s[6:7] op_sel_hi:[1,0]
	v_pk_mul_f32 v[0:1], v[0:1], s[6:7] op_sel_hi:[1,0]
	v_pk_mul_f32 v[14:15], v[14:15], s[6:7] op_sel_hi:[1,0]
	v_pk_mul_f32 v[4:5], v[4:5], s[6:7] op_sel_hi:[1,0]
	v_pk_mul_f32 v[10:11], v[10:11], s[6:7] op_sel_hi:[1,0]
	v_pk_mul_f32 v[2:3], v[2:3], s[6:7] op_sel_hi:[1,0]
	v_cvt_pk_bf16_f32 v138, v16, v17
	v_cvt_pk_bf16_f32 v139, v0, v1
	v_cvt_pk_bf16_f32 v140, v4, v5
	v_cvt_pk_bf16_f32 v141, v2, v3
	v_cvt_pk_bf16_f32 v142, v18, v19
	v_cvt_pk_bf16_f32 v143, v22, v23
	v_cvt_pk_bf16_f32 v144, v14, v15
	v_cvt_pk_bf16_f32 v145, v10, v11
	v_mov_b32_e32 v0, v81
	v_mov_b32_e32 v1, v81
	v_mov_b32_e32 v2, v81
	v_mov_b32_e32 v3, v81
	v_mov_b32_e32 v4, v81
	v_mov_b32_e32 v5, v81
	v_mov_b32_e32 v6, v81
	v_mov_b32_e32 v7, v81
	v_mov_b32_e32 v8, v81
	v_mov_b32_e32 v9, v81
	v_mov_b32_e32 v10, v81
	v_mov_b32_e32 v11, v81
	v_mov_b32_e32 v12, v81
	v_mov_b32_e32 v13, v81
	v_mov_b32_e32 v14, v81
	v_mov_b32_e32 v15, v81
	v_mov_b32_e32 v16, v81
	v_mov_b32_e32 v17, v81
	v_mov_b32_e32 v18, v81
	v_mov_b32_e32 v19, v81
	v_mov_b32_e32 v20, v81
	v_mov_b32_e32 v21, v81
	v_mov_b32_e32 v22, v81
	v_mov_b32_e32 v23, v81
	v_mov_b32_e32 v24, v81
	v_mov_b32_e32 v25, v81
	v_mov_b32_e32 v26, v81
	v_mov_b32_e32 v27, v81
	v_mov_b32_e32 v28, v81
	v_mov_b32_e32 v29, v81
	global_load_dwordx4 v[146:149], v64, s[18:19]
	global_load_dwordx4 v[150:153], v66, s[18:19]
	s_add_u32 s6, s34, s22
	s_addc_u32 s7, s35, 0
	s_add_u32 s2, s6, s20
	s_addc_u32 s3, s7, s21
	global_load_dwordx4 v[154:157], v68, s[16:17]
	global_load_dwordx4 v[158:161], v70, s[2:3]
	global_load_dwordx4 v[162:165], v72, s[2:3]
	s_or_b32 s56, s14, 64
	s_lshl_b64 s[52:53], s[56:57], 10
	s_waitcnt vmcnt(4)
	ds_write_b128 v177, v[146:149]
	v_add_u32_e32 v146, 0x200, v77
	v_lshrrev_b32_e32 v147, 4, v146
	v_mul_lo_u32 v189, v147, s23
	v_add_u32_e32 v147, v176, v189
	s_waitcnt vmcnt(3)
	ds_write_b128 v147, v[150:153]
	v_lshrrev_b32_e32 v147, 3, v77
	v_lshlrev_b32_e32 v77, 2, v77
	v_and_b32_e32 v77, 4, v77
	v_lshlrev_b32_e32 v193, 1, v77
	v_mul_lo_u32 v190, v147, s55
	v_add3_u32 v77, 0, v192, v193
	v_add_u32_e32 v78, v77, v190
	s_add_u32 s23, s28, s52
	v_add_u32_e32 v78, 0x6800, v78
	s_addc_u32 s39, s29, s53
	s_waitcnt vmcnt(1)
	ds_write2_b64 v78, v[158:159], v[160:161] offset1:2
	v_lshrrev_b32_e32 v78, 3, v146
	s_add_u32 s52, s23, s38
	v_mul_lo_u32 v194, v78, s55
	s_addc_u32 s53, s39, 0
	s_lshl_b64 s[58:59], s[56:57], 7
	v_add_u32_e32 v77, v77, v194
	s_add_u32 s60, s30, s58
	v_add3_u32 v79, 0, v190, v191
	v_add_u32_e32 v77, 0x6800, v77
	s_addc_u32 s61, s31, s59
	s_lshl_b64 s[56:57], s[56:57], 1
	ds_write_b128 v79, v[154:157] offset:17408
	s_waitcnt vmcnt(0)
	ds_write2_b64 v77, v[162:163], v[164:165] offset1:2
	s_add_u32 s62, s6, s56
	s_addc_u32 s63, s7, s57
	global_load_dwordx4 v[146:149], v64, s[52:53]
	global_load_dwordx4 v[150:153], v66, s[52:53]
	global_load_dwordx4 v[154:157], v68, s[60:61]
	global_load_dwordx4 v[158:161], v70, s[62:63]
	global_load_dwordx4 v[162:165], v72, s[62:63]
	s_add_u32 s20, s22, s20
	s_addc_u32 s21, 0, s21
	s_add_u32 s20, s20, 0x2c800100
	s_addc_u32 s21, s21, 0
	s_add_u32 s22, s4, 0x2c404000
	s_addc_u32 s23, s5, 0
	s_or_b32 s0, s0, s38
	s_add_u32 s38, s0, 0x27c20000
	s_addc_u32 s39, s1, 0
	s_mov_b64 s[58:59], 0x10000
	s_movk_i32 s57, 0x80
	v_cmp_gt_u32_e64 s[6:7], 32, v74
	v_lshl_add_u64 v[176:177], s[20:21], 0, v[70:71]
	v_lshl_add_u64 v[178:179], s[20:21], 0, v[72:73]
	v_lshl_add_u64 v[180:181], s[22:23], 0, v[68:69]
	v_lshl_add_u64 v[182:183], s[38:39], 0, v[64:65]
	v_lshl_add_u64 v[184:185], s[38:39], 0, v[66:67]
	s_mov_b32 s4, 0
	s_waitcnt lgkmcnt(0)
	s_barrier

; #define LAS __attribute__((address_space(3)))
; DI int crow(int i, int hh) { return (i & 3) + 8 * (i >> 2) + 4 * hh; }
; #define MFMA32(a, b, c) __builtin_amdgcn_mfma_f32_32x32x16_bf16((a), (b), (c), 0, 0, 0)
; DI void attn_item(CArgs& a, LAS unsigned char* lds, int l, int b, int h, int qb, int tid_, int wave, int lane_) {
;     ...
;         if (j + 2 < NT) attn_load(a, b, h, j + 2, F, kr, vr);
;         LAS bf16_t* Ks = (LAS bf16_t*)(lds + boff + AT_KS); LAS bf16_t* Rs = (LAS bf16_t*)(lds + boff + AT_RS); LAS bf16_t* Vs = (LAS bf16_t*)(lds + boff + AT_VS);
; #pragma unroll
;         for (int kt = 0; kt < 2; ++kt) {
;             f32x16 p = zero16();
; #pragma unroll
;             for (int ks = 0; ks < 8; ++ks) p = MFMA32(lds_b128(Ks + (32 * kt + r) * 136 + 16 * ks + 8 * hh), qf[ks], p);
; #pragma unroll
;             for (int ks = 0; ks < 4; ++ks) p = MFMA32(lds_b128(Rs + (32 * kt + r) * 72 + 16 * ks + 8 * hh), qf[8 + ks], p);
;             if (j >= 4 * qb) {
; #pragma unroll
;                 for (int i = 0; i < 16; ++i) { const int key = 64 * j + 32 * kt + crow(i, hh); if (key > qloc) p[i] = -INFINITY; } }
.LBB0_298:
	s_add_i32 s56, s0, 0
	v_add_u32_e32 v205, s56, v80
	v_add_u32_e32 v209, v205, v200
	v_add_u32_e32 v210, v205, v199
	ds_read_b128 v[212:215], v209
	ds_read_b128 v[226:229], v209 offset:32
	ds_read_b128 v[230:233], v209 offset:64
	ds_read_b128 v[234:237], v209 offset:96
	s_add_i32 s1, s4, 2
	s_cmp_ge_u32 s1, s54
	s_cbranch_scc1 .LBB0_300
	v_lshl_add_u64 v[64:65], s[44:45], 0, v[182:183]
	v_lshl_add_u64 v[66:67], s[44:45], 0, v[184:185]
	global_load_dwordx4 v[146:149], v[64:65], off
	global_load_dwordx4 v[150:153], v[66:67], off
	v_lshl_add_u64 v[64:65], s[44:45], 0, v[180:181]
	v_lshl_add_u64 v[66:67], s[44:45], 0, v[176:177]
	global_load_dwordx4 v[154:157], v[64:65], off
	global_load_dwordx4 v[158:161], v[66:67], off
	v_lshl_add_u64 v[64:65], s[44:45], 0, v[178:179]
	global_load_dwordx4 v[162:165], v[64:65], off
.LBB0_300:
	s_cmp_ge_u32 s4, s51
	s_cselect_b64 s[0:1], -1, 0
	s_cmp_lt_u32 s4, s51
	v_add_u32_e32 v208, s36, v195
	s_waitcnt lgkmcnt(3)
	v_mfma_f32_32x32x16_bf16 v[64:79], v[212:215], v[98:101], 0
	ds_read_b128 v[212:215], v209 offset:128
	s_waitcnt lgkmcnt(3)
	v_mfma_f32_32x32x16_bf16 v[64:79], v[226:229], v[102:105], v[64:79]
	ds_read_b128 v[226:229], v209 offset:160
	s_waitcnt lgkmcnt(3)
	v_mfma_f32_32x32x16_bf16 v[64:79], v[230:233], v[106:109], v[64:79]
	ds_read_b128 v[230:233], v209 offset:192
	s_waitcnt lgkmcnt(3)
	v_mfma_f32_32x32x16_bf16 v[64:79], v[234:237], v[110:113], v[64:79]
	ds_read_b128 v[234:237], v209 offset:224
	s_waitcnt lgkmcnt(3)
	v_mfma_f32_32x32x16_bf16 v[64:79], v[212:215], v[114:117], v[64:79]
	ds_read_b128 v[212:215], v210 offset:17408
	s_waitcnt lgkmcnt(3)
	v_mfma_f32_32x32x16_bf16 v[64:79], v[226:229], v[118:121], v[64:79]
	ds_read_b128 v[226:229], v210 offset:17440
	s_waitcnt lgkmcnt(3)
	v_mfma_f32_32x32x16_bf16 v[64:79], v[230:233], v[122:125], v[64:79]
	ds_read_b128 v[230:233], v210 offset:17472
	s_waitcnt lgkmcnt(3)
	v_mfma_f32_32x32x16_bf16 v[64:79], v[234:237], v[126:129], v[64:79]
	ds_read_b128 v[234:237], v210 offset:17504
	ds_read_b128 v[216:219], v209 offset:8704
	ds_read_b128 v[238:241], v209 offset:8736
	ds_read_b128 v[242:245], v209 offset:8768
	ds_read_b128 v[246:249], v209 offset:8800
	s_waitcnt lgkmcnt(7)
	v_mfma_f32_32x32x16_bf16 v[64:79], v[212:215], v[130:133], v[64:79]
	s_waitcnt lgkmcnt(6)
	v_mfma_f32_32x32x16_bf16 v[64:79], v[226:229], v[138:141], v[64:79]
	s_waitcnt lgkmcnt(5)
	v_mfma_f32_32x32x16_bf16 v[64:79], v[230:233], v[134:137], v[64:79]
	s_waitcnt lgkmcnt(4)
	v_mfma_f32_32x32x16_bf16 v[64:79], v[234:237], v[142:145], v[64:79]
	s_waitcnt lgkmcnt(3)
	v_mfma_f32_32x32x16_bf16 v[82:97], v[216:219], v[98:101], 0
	ds_read_b128 v[216:219], v209 offset:8832
	s_waitcnt lgkmcnt(3)
	v_mfma_f32_32x32x16_bf16 v[82:97], v[238:241], v[102:105], v[82:97]
	ds_read_b128 v[238:241], v209 offset:8864
	s_waitcnt lgkmcnt(3)
	v_mfma_f32_32x32x16_bf16 v[82:97], v[242:245], v[106:109], v[82:97]
	ds_read_b128 v[242:245], v209 offset:8896
	s_waitcnt lgkmcnt(3)
	v_mfma_f32_32x32x16_bf16 v[82:97], v[246:249], v[110:113], v[82:97]
	ds_read_b128 v[246:249], v209 offset:8928
	s_cbranch_scc1 .LBB0_302
	v_cmp_lt_i32_e32 vcc, v208, v174
	v_add_u32_e32 v205, 2, v208
	s_nop 0
	v_cndmask_b32_e32 v65, v223, v65, vcc
	v_cmp_le_i32_e32 vcc, v208, v174
	s_nop 1
	v_cndmask_b32_e32 v64, v223, v64, vcc
	v_cmp_le_i32_e32 vcc, v205, v174
	v_add_u32_e32 v205, 3, v208
	s_nop 0
	v_cndmask_b32_e32 v66, v223, v66, vcc
	v_cmp_le_i32_e32 vcc, v205, v174
	v_add_u32_e32 v205, 8, v208
	s_nop 0
	v_cndmask_b32_e32 v67, v223, v67, vcc
	v_cmp_le_i32_e32 vcc, v205, v174
	v_add_u32_e32 v205, 9, v208
	s_nop 0
	v_cndmask_b32_e32 v68, v223, v68, vcc
	v_cmp_le_i32_e32 vcc, v205, v174
	v_add_u32_e32 v205, 10, v208
	s_nop 0
	v_cndmask_b32_e32 v69, v223, v69, vcc
	v_cmp_le_i32_e32 vcc, v205, v174
	v_add_u32_e32 v205, 11, v208
	s_nop 0
	v_cndmask_b32_e32 v70, v223, v70, vcc
	v_cmp_le_i32_e32 vcc, v205, v174
	v_add_u32_e32 v205, 16, v208
	s_nop 0
	v_cndmask_b32_e32 v71, v223, v71, vcc
	v_cmp_le_i32_e32 vcc, v205, v174
	v_add_u32_e32 v205, 17, v208
	s_nop 0
	v_cndmask_b32_e32 v72, v223, v72, vcc
	v_cmp_le_i32_e32 vcc, v205, v174
	v_add_u32_e32 v205, 18, v208
	s_nop 0
	v_cndmask_b32_e32 v73, v223, v73, vcc
	v_cmp_le_i32_e32 vcc, v205, v174
	v_add_u32_e32 v205, 19, v208
	s_nop 0
	v_cndmask_b32_e32 v74, v223, v74, vcc
	v_cmp_le_i32_e32 vcc, v205, v174
	v_add_u32_e32 v205, 24, v208
	s_nop 0
	v_cndmask_b32_e32 v75, v223, v75, vcc
	v_cmp_le_i32_e32 vcc, v205, v174
	v_add_u32_e32 v205, 25, v208
	s_nop 0
	v_cndmask_b32_e32 v76, v223, v76, vcc
	v_cmp_le_i32_e32 vcc, v205, v174
	v_add_u32_e32 v205, 26, v208
	s_nop 0
	v_cndmask_b32_e32 v77, v223, v77, vcc
	v_cmp_le_i32_e32 vcc, v205, v174
	v_add_u32_e32 v205, 27, v208
	s_nop 0
	v_cndmask_b32_e32 v78, v223, v78, vcc
	v_cmp_le_i32_e32 vcc, v205, v174
	s_nop 1
	v_cndmask_b32_e32 v79, v223, v79, vcc
; DI float shx(float v, int o, int lane) { return __int_as_float(__builtin_amdgcn_ds_bpermute((lane ^ o) << 2, __float_as_int(v))); }
; DI int crow(int i, int hh) { return (i & 3) + 8 * (i >> 2) + 4 * hh; }
; #define MFMA32(a, b, c) __builtin_amdgcn_mfma_f32_32x32x16_bf16((a), (b), (c), 0, 0, 0)
; DI void attn_item(CArgs& a, LAS unsigned char* lds, int l, int b, int h, int qb, int tid_, int wave, int lane_) {
;     ...
;             float tmax = p[0];
; #pragma unroll
;             for (int i = 1; i < 16; ++i) tmax = fmaxf(tmax, p[i]);
;             tmax = fmaxf(tmax, shx(tmax, 32, lane));
;             const float m_new = fmaxf(m_run, tmax), alpha = __builtin_amdgcn_exp2f(m_run - m_new); m_run = m_new;
;             float rsum = 0.f;
; #pragma unroll
;             for (int i = 0; i < 16; ++i) { const float e = __builtin_amdgcn_exp2f(p[i] - m_new); p[i] = e; rsum += e; }
;             l_run = l_run * alpha + rsum;
;             if (__any(alpha != 1.f)) {
;                 if (hh == 0) scr[r] = alpha;
;                 asm volatile("s_waitcnt lgkmcnt(0)" ::: "memory");
; #pragma unroll
;                 for (int i = 0; i < 16; ++i) { const float ai = scr[crow(i, hh)]; o[0][i] *= ai; o[1][i] *= ai; o[2][i] *= ai; o[3][i] *= ai; }
;             }
;             const bf16x8 pa0 = packstep<0>(p), pa1 = packstep<1>(p);
; #pragma unroll
;             for (int vt = 0; vt < 4; ++vt) {
;                 o[vt] = MFMA32(pa0, lds_b128(Vs + (32 * vt + r) * 72 + 32 * kt + 8 * hh), o[vt]);
;                 o[vt] = MFMA32(pa1, lds_b128(Vs + (32 * vt + r) * 72 + 32 * kt + 16 + 8 * hh), o[vt]); }
;         }
.LBB0_302:
	v_max_f32_e32 v205, v65, v65
	v_max_f32_e32 v206, v64, v64
	v_max_f32_e32 v205, v206, v205
	s_waitcnt lgkmcnt(3)
	v_mfma_f32_32x32x16_bf16 v[82:97], v[216:219], v[114:117], v[82:97]
	ds_read_b128 v[216:219], v210 offset:22016
	v_max3_f32 v205, v205, v66, v67
	v_max3_f32 v205, v205, v68, v69
	v_max3_f32 v205, v205, v70, v71
	v_max3_f32 v205, v205, v72, v73
	s_waitcnt lgkmcnt(3)
	v_mfma_f32_32x32x16_bf16 v[82:97], v[238:241], v[118:121], v[82:97]
	ds_read_b128 v[238:241], v210 offset:22048
	v_max3_f32 v205, v205, v74, v75
	v_max3_f32 v205, v205, v76, v77
	v_max3_f32 v205, v205, v78, v79
	ds_bpermute_b32 v206, v198, v205
	s_waitcnt lgkmcnt(4)
	v_mfma_f32_32x32x16_bf16 v[82:97], v[242:245], v[122:125], v[82:97]
	ds_read_b128 v[242:245], v210 offset:22080
	s_waitcnt lgkmcnt(4)
	v_mfma_f32_32x32x16_bf16 v[82:97], v[246:249], v[126:129], v[82:97]
	ds_read_b128 v[246:249], v210 offset:22112
	s_waitcnt lgkmcnt(2)
	v_max3_f32 v211, v204, v205, v206
	v_sub_f32_e32 v204, v204, v211
	v_exp_f32_e32 v206, v204
	s_nop 0
	v_cmp_neq_f32_e32 vcc, 1.0, v206
	s_cbranch_vccz .LBB0_306
	s_and_saveexec_b64 s[4:5], s[6:7]
	ds_write_b32 v197, v206
	s_or_b64 exec, exec, s[4:5]
	s_waitcnt lgkmcnt(0)
	v_add_u32_e32 v204, s27, v80
	ds_read_b128 v[212:215], v204 offset:96
	ds_read_b128 v[226:229], v204 offset:64
	ds_read_b128 v[230:233], v204 offset:32
	ds_read_b128 v[234:237], v204
	s_mov_b64 s[58:59], 0x10000
	s_waitcnt lgkmcnt(3)
	v_pk_mul_f32 v[12:13], v[12:13], v[212:213]
	s_waitcnt lgkmcnt(2)
	v_pk_mul_f32 v[8:9], v[8:9], v[226:227]
	s_waitcnt lgkmcnt(1)
	v_pk_mul_f32 v[4:5], v[4:5], v[230:231]
	v_pk_mul_f32 v[14:15], v[14:15], v[214:215]
	v_pk_mul_f32 v[10:11], v[10:11], v[228:229]
	v_pk_mul_f32 v[6:7], v[6:7], v[232:233]
	s_waitcnt lgkmcnt(0)
	v_pk_mul_f32 v[2:3], v[2:3], v[236:237]
	v_pk_mul_f32 v[0:1], v[0:1], v[234:235]
	v_pk_mul_f32 v[28:29], v[28:29], v[212:213]
	v_pk_mul_f32 v[24:25], v[24:25], v[226:227]
	v_pk_mul_f32 v[20:21], v[20:21], v[230:231]
	v_pk_mul_f32 v[30:31], v[30:31], v[214:215]
	v_pk_mul_f32 v[26:27], v[26:27], v[228:229]
	v_pk_mul_f32 v[22:23], v[22:23], v[232:233]
	v_pk_mul_f32 v[18:19], v[18:19], v[236:237]
	v_pk_mul_f32 v[16:17], v[16:17], v[234:235]
	v_pk_mul_f32 v[44:45], v[44:45], v[212:213]
	v_pk_mul_f32 v[40:41], v[40:41], v[226:227]
	v_pk_mul_f32 v[36:37], v[36:37], v[230:231]
	v_pk_mul_f32 v[46:47], v[46:47], v[214:215]
	v_pk_mul_f32 v[42:43], v[42:43], v[228:229]
	v_pk_mul_f32 v[38:39], v[38:39], v[232:233]
	v_pk_mul_f32 v[34:35], v[34:35], v[236:237]
	v_pk_mul_f32 v[32:33], v[32:33], v[234:235]
	v_pk_mul_f32 v[60:61], v[60:61], v[212:213]
	v_pk_mul_f32 v[56:57], v[56:57], v[226:227]
	v_pk_mul_f32 v[52:53], v[52:53], v[230:231]
	v_pk_mul_f32 v[62:63], v[62:63], v[214:215]
	v_pk_mul_f32 v[58:59], v[58:59], v[228:229]
	v_pk_mul_f32 v[54:55], v[54:55], v[232:233]
	v_pk_mul_f32 v[50:51], v[50:51], v[236:237]
	v_pk_mul_f32 v[48:49], v[48:49], v[234:235]
.LBB0_306:
	v_add3_u32 v205, s56, v199, v202
	v_add3_u32 v207, s56, v201, v202
	v_sub_f32_e32 v64, v64, v211
	v_exp_f32_e32 v212, v64
	v_sub_f32_e32 v64, v65, v211
	v_exp_f32_e32 v213, v64
	v_sub_f32_e32 v64, v66, v211
	v_exp_f32_e32 v214, v64
	v_sub_f32_e32 v64, v67, v211
	v_exp_f32_e32 v215, v64
	s_waitcnt lgkmcnt(4)
	v_mfma_f32_32x32x16_bf16 v[82:97], v[216:219], v[130:133], v[82:97]
	ds_read_b128 v[216:219], v205 offset:26624
	v_sub_f32_e32 v64, v68, v211
	v_exp_f32_e32 v225, v64
	v_sub_f32_e32 v64, v69, v211
	v_exp_f32_e32 v226, v64
	v_sub_f32_e32 v64, v70, v211
	v_exp_f32_e32 v227, v64
	v_sub_f32_e32 v64, v71, v211
	v_exp_f32_e32 v228, v64
	s_waitcnt lgkmcnt(4)
	v_mfma_f32_32x32x16_bf16 v[82:97], v[238:241], v[138:141], v[82:97]
	ds_read_b128 v[238:241], v207 offset:26624
	v_sub_f32_e32 v64, v72, v211
	v_exp_f32_e32 v229, v64
	v_sub_f32_e32 v64, v73, v211
	v_exp_f32_e32 v230, v64
	v_sub_f32_e32 v64, v74, v211
	v_exp_f32_e32 v231, v64
	v_sub_f32_e32 v64, v75, v211
	v_exp_f32_e32 v232, v64
	s_waitcnt lgkmcnt(3)
	v_mfma_f32_32x32x16_bf16 v[82:97], v[242:245], v[134:137], v[82:97]
	ds_read_b128 v[242:245], v205 offset:35840
	v_sub_f32_e32 v64, v76, v211
	v_exp_f32_e32 v233, v64
	v_sub_f32_e32 v64, v77, v211
	v_exp_f32_e32 v234, v64
	v_sub_f32_e32 v64, v78, v211
	v_exp_f32_e32 v235, v64
	v_sub_f32_e32 v72, v79, v211
	v_exp_f32_e32 v236, v72
	s_waitcnt lgkmcnt(3)
	v_mfma_f32_32x32x16_bf16 v[82:97], v[246:249], v[142:145], v[82:97]
	ds_read_b128 v[246:249], v205 offset:40448
	v_cvt_pk_bf16_f32 v64, v212, v213
	v_cvt_pk_bf16_f32 v65, v214, v215
	v_cvt_pk_bf16_f32 v66, v225, v226
	v_cvt_pk_bf16_f32 v67, v227, v228
	v_cvt_pk_bf16_f32 v72, v229, v230
	v_cvt_pk_bf16_f32 v73, v231, v232
	v_cvt_pk_bf16_f32 v74, v233, v234
	v_cvt_pk_bf16_f32 v75, v235, v236
	ds_read_b128 v[68:71], v205 offset:26656
	ds_read_b128 v[76:79], v207 offset:26656
	s_waitcnt lgkmcnt(5)
	v_mfma_f32_32x32x16_bf16 v[0:15], v[64:67], v[216:219], v[0:15]
	ds_read_b128 v[216:219], v205 offset:35872
	s_waitcnt lgkmcnt(5)
	v_mfma_f32_32x32x16_bf16 v[16:31], v[64:67], v[238:241], v[16:31]
	ds_read_b128 v[238:241], v205 offset:40480
	s_waitcnt lgkmcnt(5)
	v_mfma_f32_32x32x16_bf16 v[32:47], v[64:67], v[242:245], v[32:47]
	s_waitcnt lgkmcnt(4)
	v_mfma_f32_32x32x16_bf16 v[48:63], v[64:67], v[246:249], v[48:63]
	s_andn2_b64 vcc, exec, s[0:1]
	s_cbranch_vccnz .LBB0_308
; DI float shx(float v, int o, int lane) { return __int_as_float(__builtin_amdgcn_ds_bpermute((lane ^ o) << 2, __float_as_int(v))); }
; DI int crow(int i, int hh) { return (i & 3) + 8 * (i >> 2) + 4 * hh; }
; #define MFMA32(a, b, c) __builtin_amdgcn_mfma_f32_32x32x16_bf16((a), (b), (c), 0, 0, 0)
; DI void attn_item(CArgs& a, LAS unsigned char* lds, int l, int b, int h, int qb, int tid_, int wave, int lane_) {
;     ...
;             if (j >= 4 * qb) {
; #pragma unroll
;                 for (int i = 0; i < 16; ++i) { const int key = 64 * j + 32 * kt + crow(i, hh); if (key > qloc) p[i] = -INFINITY; } }
;             float tmax = p[0];
; #pragma unroll
;             for (int i = 1; i < 16; ++i) tmax = fmaxf(tmax, p[i]);
;             tmax = fmaxf(tmax, shx(tmax, 32, lane));
;             const float m_new = fmaxf(m_run, tmax), alpha = __builtin_amdgcn_exp2f(m_run - m_new); m_run = m_new;
;             float rsum = 0.f;
; #pragma unroll
;             for (int i = 0; i < 16; ++i) { const float e = __builtin_amdgcn_exp2f(p[i] - m_new); p[i] = e; rsum += e; }
;             l_run = l_run * alpha + rsum;
;             if (__any(alpha != 1.f)) {
;                 if (hh == 0) scr[r] = alpha;
;                 asm volatile("s_waitcnt lgkmcnt(0)" ::: "memory");
; #pragma unroll
;                 for (int i = 0; i < 16; ++i) { const float ai = scr[crow(i, hh)]; o[0][i] *= ai; o[1][i] *= ai; o[2][i] *= ai; o[3][i] *= ai; }
;             }
;             const bf16x8 pa0 = packstep<0>(p), pa1 = packstep<1>(p);
; #pragma unroll
;             for (int vt = 0; vt < 4; ++vt) {
;                 o[vt] = MFMA32(pa0, lds_b128(Vs + (32 * vt + r) * 72 + 32 * kt + 8 * hh), o[vt]);
;                 o[vt] = MFMA32(pa1, lds_b128(Vs + (32 * vt + r) * 72 + 32 * kt + 16 + 8 * hh), o[vt]); }
;         }
	v_add_u32_e32 v204, 32, v208
	v_cmp_le_i32_e32 vcc, v204, v174
	v_add_u32_e32 v204, 33, v208
	s_nop 0
	v_cndmask_b32_e32 v82, v223, v82, vcc
	v_cmp_le_i32_e32 vcc, v204, v174
	v_add_u32_e32 v204, 34, v208
	s_nop 0
	v_cndmask_b32_e32 v83, v223, v83, vcc
	v_cmp_le_i32_e32 vcc, v204, v174
	v_add_u32_e32 v204, 35, v208
	s_nop 0
	v_cndmask_b32_e32 v84, v223, v84, vcc
	v_cmp_le_i32_e32 vcc, v204, v174
	v_add_u32_e32 v204, 40, v208
	s_nop 0
	v_cndmask_b32_e32 v85, v223, v85, vcc
	v_cmp_le_i32_e32 vcc, v204, v174
	v_add_u32_e32 v204, 41, v208
	s_nop 0
	v_cndmask_b32_e32 v86, v223, v86, vcc
	v_cmp_le_i32_e32 vcc, v204, v174
	v_add_u32_e32 v204, 42, v208
	s_nop 0
	v_cndmask_b32_e32 v87, v223, v87, vcc
	v_cmp_le_i32_e32 vcc, v204, v174
	v_add_u32_e32 v204, 43, v208
	s_nop 0
	v_cndmask_b32_e32 v88, v223, v88, vcc
	v_cmp_le_i32_e32 vcc, v204, v174
	v_add_u32_e32 v204, 48, v208
	s_nop 0
	v_cndmask_b32_e32 v89, v223, v89, vcc
	v_cmp_le_i32_e32 vcc, v204, v174
	v_add_u32_e32 v204, 49, v208
	s_nop 0
	v_cndmask_b32_e32 v90, v223, v90, vcc
	v_cmp_le_i32_e32 vcc, v204, v174
	v_add_u32_e32 v204, 50, v208
	s_nop 0
	v_cndmask_b32_e32 v91, v223, v91, vcc
	v_cmp_le_i32_e32 vcc, v204, v174
	v_add_u32_e32 v204, 51, v208
	s_nop 0
	v_cndmask_b32_e32 v92, v223, v92, vcc
	v_cmp_le_i32_e32 vcc, v204, v174
	v_add_u32_e32 v204, 56, v208
	s_nop 0
	v_cndmask_b32_e32 v93, v223, v93, vcc
	v_cmp_le_i32_e32 vcc, v204, v174
	v_add_u32_e32 v204, 57, v208
	s_nop 0
	v_cndmask_b32_e32 v94, v223, v94, vcc
	v_cmp_le_i32_e32 vcc, v204, v174
	v_add_u32_e32 v204, 58, v208
	s_nop 0
	v_cndmask_b32_e32 v95, v223, v95, vcc
	v_cmp_le_i32_e32 vcc, v204, v174
	v_add_u32_e32 v204, 59, v208
	s_nop 0
	v_cndmask_b32_e32 v96, v223, v96, vcc
	v_cmp_le_i32_e32 vcc, v204, v174
	s_nop 1
	v_cndmask_b32_e32 v97, v223, v97, vcc
.LBB0_308:
	v_max_f32_e32 v204, v83, v83
	v_max_f32_e32 v208, v82, v82
	v_max_f32_e32 v204, v208, v204
	s_waitcnt lgkmcnt(3)
	v_mfma_f32_32x32x16_bf16 v[0:15], v[72:75], v[68:71], v[0:15]
	v_max3_f32 v204, v204, v84, v85
	v_max3_f32 v204, v204, v86, v87
	v_max3_f32 v204, v204, v88, v89
	v_max3_f32 v204, v204, v90, v91
	s_waitcnt lgkmcnt(2)
	v_mfma_f32_32x32x16_bf16 v[16:31], v[72:75], v[76:79], v[16:31]
	v_max3_f32 v204, v204, v92, v93
	v_max3_f32 v204, v204, v94, v95
	v_max3_f32 v204, v204, v96, v97
	ds_bpermute_b32 v208, v198, v204
	s_waitcnt lgkmcnt(2)
	v_mfma_f32_32x32x16_bf16 v[32:47], v[72:75], v[216:219], v[32:47]
	s_waitcnt lgkmcnt(1)
	v_mfma_f32_32x32x16_bf16 v[48:63], v[72:75], v[238:241], v[48:63]
	s_waitcnt lgkmcnt(0)
	v_max3_f32 v204, v211, v204, v208
	v_sub_f32_e32 v208, v211, v204
	v_exp_f32_e32 v208, v208
	s_nop 0
	v_cmp_neq_f32_e32 vcc, 1.0, v208
	s_cbranch_vccz .LBB0_312
	s_and_saveexec_b64 s[0:1], s[6:7]
	ds_write_b32 v197, v208
	s_or_b64 exec, exec, s[0:1]
	s_waitcnt lgkmcnt(0)
	v_add_u32_e32 v209, s27, v80
	ds_read_b128 v[238:241], v209 offset:96
	ds_read_b128 v[242:245], v209 offset:64
	ds_read_b128 v[246:249], v209 offset:32
	ds_read_b128 v[216:219], v209
	s_waitcnt lgkmcnt(3)
	v_pk_mul_f32 v[12:13], v[12:13], v[238:239]
	s_waitcnt lgkmcnt(2)
	v_pk_mul_f32 v[8:9], v[8:9], v[242:243]
	s_waitcnt lgkmcnt(1)
	v_pk_mul_f32 v[4:5], v[4:5], v[246:247]
	v_pk_mul_f32 v[14:15], v[14:15], v[240:241]
	v_pk_mul_f32 v[10:11], v[10:11], v[244:245]
	v_pk_mul_f32 v[6:7], v[6:7], v[248:249]
	s_waitcnt lgkmcnt(0)
	v_pk_mul_f32 v[2:3], v[2:3], v[218:219]
	v_pk_mul_f32 v[0:1], v[0:1], v[216:217]
	v_pk_mul_f32 v[28:29], v[28:29], v[238:239]
	v_pk_mul_f32 v[24:25], v[24:25], v[242:243]
	v_pk_mul_f32 v[20:21], v[20:21], v[246:247]
	v_pk_mul_f32 v[30:31], v[30:31], v[240:241]
	v_pk_mul_f32 v[26:27], v[26:27], v[244:245]
	v_pk_mul_f32 v[22:23], v[22:23], v[248:249]
	v_pk_mul_f32 v[18:19], v[18:19], v[218:219]
	v_pk_mul_f32 v[16:17], v[16:17], v[216:217]
	v_pk_mul_f32 v[44:45], v[44:45], v[238:239]
	v_pk_mul_f32 v[40:41], v[40:41], v[242:243]
	v_pk_mul_f32 v[36:37], v[36:37], v[246:247]
	v_pk_mul_f32 v[46:47], v[46:47], v[240:241]
	v_pk_mul_f32 v[42:43], v[42:43], v[244:245]
	v_pk_mul_f32 v[38:39], v[38:39], v[248:249]
	v_pk_mul_f32 v[34:35], v[34:35], v[218:219]
	v_pk_mul_f32 v[32:33], v[32:33], v[216:217]
	v_pk_mul_f32 v[60:61], v[60:61], v[238:239]
	v_pk_mul_f32 v[56:57], v[56:57], v[242:243]
	v_pk_mul_f32 v[52:53], v[52:53], v[246:247]
	v_pk_mul_f32 v[62:63], v[62:63], v[240:241]
	v_pk_mul_f32 v[58:59], v[58:59], v[244:245]
	v_pk_mul_f32 v[54:55], v[54:55], v[248:249]
	v_pk_mul_f32 v[50:51], v[50:51], v[218:219]
	v_pk_mul_f32 v[48:49], v[48:49], v[216:217]
; DI int crow(int i, int hh) { return (i & 3) + 8 * (i >> 2) + 4 * hh; }
; #define MFMA32(a, b, c) __builtin_amdgcn_mfma_f32_32x32x16_bf16((a), (b), (c), 0, 0, 0)
; DI void attn_item(CArgs& a, LAS unsigned char* lds, int l, int b, int h, int qb, int tid_, int wave, int lane_) {
;     ...
;             float rsum = 0.f;
; #pragma unroll
;             for (int i = 0; i < 16; ++i) { const float e = __builtin_amdgcn_exp2f(p[i] - m_new); p[i] = e; rsum += e; }
;             l_run = l_run * alpha + rsum;
;             if (__any(alpha != 1.f)) {
;                 if (hh == 0) scr[r] = alpha;
;                 asm volatile("s_waitcnt lgkmcnt(0)" ::: "memory");
; #pragma unroll
;                 for (int i = 0; i < 16; ++i) { const float ai = scr[crow(i, hh)]; o[0][i] *= ai; o[1][i] *= ai; o[2][i] *= ai; o[3][i] *= ai; }
;             }
;             const bf16x8 pa0 = packstep<0>(p), pa1 = packstep<1>(p);
; #pragma unroll
;             for (int vt = 0; vt < 4; ++vt) {
;                 o[vt] = MFMA32(pa0, lds_b128(Vs + (32 * vt + r) * 72 + 32 * kt + 8 * hh), o[vt]);
;                 o[vt] = MFMA32(pa1, lds_b128(Vs + (32 * vt + r) * 72 + 32 * kt + 16 + 8 * hh), o[vt]); }
;         }
;         __syncthreads();
.LBB0_312:
	ds_read_b128 v[242:245], v205 offset:26688
	ds_read_b128 v[246:249], v207 offset:26688
	ds_read_b128 v[216:219], v205 offset:35904
	ds_read_b128 v[238:241], v205 offset:40512
	v_add_f32_e32 v209, 0, v212
	v_add_f32_e32 v209, v213, v209
	v_add_f32_e32 v209, v214, v209
	v_add_f32_e32 v209, v215, v209
	v_add_f32_e32 v209, v225, v209
	v_add_f32_e32 v209, v226, v209
	v_add_f32_e32 v209, v227, v209
	v_add_f32_e32 v209, v228, v209
	v_add_f32_e32 v209, v229, v209
	v_add_f32_e32 v209, v230, v209
	v_add_f32_e32 v209, v231, v209
	v_add_f32_e32 v209, v232, v209
	v_sub_f32_e32 v82, v82, v204
	v_add_f32_e32 v209, v233, v209
	v_exp_f32_e32 v82, v82
	v_sub_f32_e32 v83, v83, v204
	v_add_f32_e32 v209, v234, v209
	v_exp_f32_e32 v83, v83
	v_sub_f32_e32 v84, v84, v204
	v_add_f32_e32 v209, v235, v209
	v_exp_f32_e32 v84, v84
	v_sub_f32_e32 v85, v85, v204
	v_add_f32_e32 v209, v236, v209
	v_exp_f32_e32 v85, v85
	v_sub_f32_e32 v86, v86, v204
	v_fmac_f32_e32 v209, v203, v206
	v_add_f32_e32 v203, 0, v82
	v_exp_f32_e32 v86, v86
	v_sub_f32_e32 v87, v87, v204
	v_add_f32_e32 v203, v83, v203
	v_exp_f32_e32 v87, v87
	v_sub_f32_e32 v88, v88, v204
	v_add_f32_e32 v203, v84, v203
	v_exp_f32_e32 v88, v88
	v_sub_f32_e32 v89, v89, v204
	v_add_f32_e32 v203, v85, v203
	v_exp_f32_e32 v89, v89
	v_sub_f32_e32 v90, v90, v204
	v_add_f32_e32 v203, v86, v203
	v_exp_f32_e32 v90, v90
	v_sub_f32_e32 v91, v91, v204
	v_add_f32_e32 v203, v87, v203
	v_exp_f32_e32 v91, v91
	v_sub_f32_e32 v92, v92, v204
	v_add_f32_e32 v203, v88, v203
	v_exp_f32_e32 v92, v92
	v_sub_f32_e32 v93, v93, v204
	v_add_f32_e32 v203, v89, v203
	v_exp_f32_e32 v93, v93
	v_sub_f32_e32 v94, v94, v204
	v_add_f32_e32 v203, v90, v203
	v_exp_f32_e32 v94, v94
	v_sub_f32_e32 v95, v95, v204
	v_add_f32_e32 v203, v91, v203
	v_exp_f32_e32 v95, v95
	v_sub_f32_e32 v96, v96, v204
	v_add_f32_e32 v203, v92, v203
	v_exp_f32_e32 v96, v96
	v_sub_f32_e32 v97, v97, v204
	v_add_f32_e32 v203, v93, v203
	v_exp_f32_e32 v97, v97
	v_add_f32_e32 v203, v94, v203
	v_add_f32_e32 v203, v95, v203
	v_add_f32_e32 v203, v96, v203
	v_cvt_pk_bf16_f32 v82, v82, v83
	v_cvt_pk_bf16_f32 v83, v84, v85
	v_cvt_pk_bf16_f32 v84, v86, v87
	v_cvt_pk_bf16_f32 v85, v88, v89
	v_add_f32_e32 v203, v97, v203
	v_cvt_pk_bf16_f32 v86, v90, v91
	v_cvt_pk_bf16_f32 v87, v92, v93
	v_cvt_pk_bf16_f32 v88, v94, v95
	v_cvt_pk_bf16_f32 v89, v96, v97
	ds_read_b128 v[90:93], v205 offset:26720
	ds_read_b128 v[94:97], v207 offset:26720
	s_waitcnt lgkmcnt(5)
	v_mfma_f32_32x32x16_bf16 v[0:15], v[82:85], v[242:245], v[0:15]
	ds_read_b128 v[242:245], v205 offset:35936
	s_add_i32 s36, s36, 64
	s_mov_b64 s[0:1], 0x2000
	v_fmac_f32_e32 v203, v209, v208
	s_waitcnt lgkmcnt(5)
	v_mfma_f32_32x32x16_bf16 v[16:31], v[82:85], v[246:249], v[16:31]
	ds_read_b128 v[246:249], v205 offset:40544
	v_lshl_add_u64 v[176:177], v[176:177], 0, s[68:69]
	v_lshl_add_u64 v[178:179], v[178:179], 0, s[68:69]
	s_waitcnt lgkmcnt(5)
	v_mfma_f32_32x32x16_bf16 v[32:47], v[82:85], v[216:219], v[32:47]
	v_lshl_add_u64 v[180:181], v[180:181], 0, s[0:1]
	v_lshl_add_u64 v[182:183], v[182:183], 0, s[58:59]
	s_waitcnt lgkmcnt(4)
	v_mfma_f32_32x32x16_bf16 v[48:63], v[82:85], v[238:241], v[48:63]
	v_lshl_add_u64 v[184:185], v[184:185], 0, s[58:59]
	s_cmp_eq_u32 s50, s36
	s_waitcnt lgkmcnt(3)
	v_mfma_f32_32x32x16_bf16 v[0:15], v[86:89], v[90:93], v[0:15]
	s_waitcnt lgkmcnt(2)
	v_mfma_f32_32x32x16_bf16 v[16:31], v[86:89], v[94:97], v[16:31]
	s_waitcnt lgkmcnt(0)
	s_barrier
	v_mfma_f32_32x32x16_bf16 v[32:47], v[86:89], v[242:245], v[32:47]
	v_mfma_f32_32x32x16_bf16 v[48:63], v[86:89], v[246:249], v[48:63]
	s_cbranch_scc1 .LBB0_314
	s_mov_b32 s4, s55
	s_branch .LBB0_296

; #define LAS __attribute__((address_space(3)))
; DI int crow(int i, int hh) { return (i & 3) + 8 * (i >> 2) + 4 * hh; }
; #define MFMA32(a, b, c) __builtin_amdgcn_mfma_f32_32x32x16_bf16((a), (b), (c), 0, 0, 0)
; DI void attn_item(CArgs& a, LAS unsigned char* lds, int l, int b, int h, int qb, int tid_, int wave, int lane_) {
;     ...
;         if (j + 2 < NT) attn_load(a, b, h, j + 2, F, kr, vr);
;         LAS bf16_t* Ks = (LAS bf16_t*)(lds + boff + AT_KS); LAS bf16_t* Rs = (LAS bf16_t*)(lds + boff + AT_RS); LAS bf16_t* Vs = (LAS bf16_t*)(lds + boff + AT_VS);
; #pragma unroll
;         for (int kt = 0; kt < 2; ++kt) {
;             f32x16 p = zero16();
; #pragma unroll
;             for (int ks = 0; ks < 8; ++ks) p = MFMA32(lds_b128(Ks + (32 * kt + r) * 136 + 16 * ks + 8 * hh), qf[ks], p);
; #pragma unroll
;             for (int ks = 0; ks < 4; ++ks) p = MFMA32(lds_b128(Rs + (32 * kt + r) * 72 + 16 * ks + 8 * hh), qf[8 + ks], p);
;             if (j >= 4 * qb) {
; #pragma unroll
;                 for (int i = 0; i < 16; ++i) { const int key = 64 * j + 32 * kt + crow(i, hh); if (key > qloc) p[i] = -INFINITY; } }
.LBB0_319:
	s_add_i32 s18, s0, 0
	v_add_u32_e32 v205, s18, v80
	v_add_u32_e32 v209, v205, v200
	v_add_u32_e32 v210, v205, v199
	ds_read_b128 v[212:215], v209
	ds_read_b128 v[226:229], v209 offset:32
	ds_read_b128 v[230:233], v209 offset:64
	ds_read_b128 v[234:237], v209 offset:96
	s_add_i32 s1, s2, 2
	s_cmp_ge_u32 s1, s47
	s_cbranch_scc1 .LBB0_321
	v_lshl_add_u64 v[64:65], s[44:45], 0, v[182:183]
	v_lshl_add_u64 v[66:67], s[44:45], 0, v[184:185]
	global_load_dwordx4 v[146:149], v[64:65], off
	global_load_dwordx4 v[150:153], v[66:67], off
	v_lshl_add_u64 v[64:65], s[44:45], 0, v[180:181]
	v_lshl_add_u64 v[66:67], s[44:45], 0, v[176:177]
	global_load_dwordx4 v[154:157], v[64:65], off
	global_load_dwordx4 v[158:161], v[66:67], off
	v_lshl_add_u64 v[64:65], s[44:45], 0, v[178:179]
	global_load_dwordx4 v[162:165], v[64:65], off
.LBB0_321:
	s_cmp_ge_u32 s2, s36
	s_cselect_b64 s[0:1], -1, 0
	s_cmp_lt_u32 s2, s36
	v_add_u32_e32 v208, s4, v195
	s_waitcnt lgkmcnt(3)
	v_mfma_f32_32x32x16_bf16 v[64:79], v[212:215], v[98:101], 0
	ds_read_b128 v[212:215], v209 offset:128
	s_waitcnt lgkmcnt(3)
	v_mfma_f32_32x32x16_bf16 v[64:79], v[226:229], v[102:105], v[64:79]
	ds_read_b128 v[226:229], v209 offset:160
	s_waitcnt lgkmcnt(3)
	v_mfma_f32_32x32x16_bf16 v[64:79], v[230:233], v[106:109], v[64:79]
	ds_read_b128 v[230:233], v209 offset:192
	s_waitcnt lgkmcnt(3)
	v_mfma_f32_32x32x16_bf16 v[64:79], v[234:237], v[110:113], v[64:79]
	ds_read_b128 v[234:237], v209 offset:224
	s_waitcnt lgkmcnt(3)
	v_mfma_f32_32x32x16_bf16 v[64:79], v[212:215], v[114:117], v[64:79]
	ds_read_b128 v[212:215], v210 offset:17408
	s_waitcnt lgkmcnt(3)
	v_mfma_f32_32x32x16_bf16 v[64:79], v[226:229], v[118:121], v[64:79]
	ds_read_b128 v[226:229], v210 offset:17440
	s_waitcnt lgkmcnt(3)
	v_mfma_f32_32x32x16_bf16 v[64:79], v[230:233], v[122:125], v[64:79]
	ds_read_b128 v[230:233], v210 offset:17472
	s_waitcnt lgkmcnt(3)
	v_mfma_f32_32x32x16_bf16 v[64:79], v[234:237], v[126:129], v[64:79]
	ds_read_b128 v[234:237], v210 offset:17504
	ds_read_b128 v[216:219], v209 offset:8704
	ds_read_b128 v[238:241], v209 offset:8736
	ds_read_b128 v[242:245], v209 offset:8768
	ds_read_b128 v[246:249], v209 offset:8800
	s_waitcnt lgkmcnt(7)
	v_mfma_f32_32x32x16_bf16 v[64:79], v[212:215], v[130:133], v[64:79]
	s_waitcnt lgkmcnt(6)
	v_mfma_f32_32x32x16_bf16 v[64:79], v[226:229], v[138:141], v[64:79]
	s_waitcnt lgkmcnt(5)
	v_mfma_f32_32x32x16_bf16 v[64:79], v[230:233], v[134:137], v[64:79]
	s_waitcnt lgkmcnt(4)
	v_mfma_f32_32x32x16_bf16 v[64:79], v[234:237], v[142:145], v[64:79]
	s_waitcnt lgkmcnt(3)
	v_mfma_f32_32x32x16_bf16 v[82:97], v[216:219], v[98:101], 0
	ds_read_b128 v[216:219], v209 offset:8832
	s_waitcnt lgkmcnt(3)
	v_mfma_f32_32x32x16_bf16 v[82:97], v[238:241], v[102:105], v[82:97]
	ds_read_b128 v[238:241], v209 offset:8864
	s_waitcnt lgkmcnt(3)
	v_mfma_f32_32x32x16_bf16 v[82:97], v[242:245], v[106:109], v[82:97]
	ds_read_b128 v[242:245], v209 offset:8896
	s_waitcnt lgkmcnt(3)
	v_mfma_f32_32x32x16_bf16 v[82:97], v[246:249], v[110:113], v[82:97]
	ds_read_b128 v[246:249], v209 offset:8928
	s_cbranch_scc1 .LBB0_323
	v_cmp_lt_i32_e32 vcc, v208, v174
	v_add_u32_e32 v205, 2, v208
	s_nop 0
	v_cndmask_b32_e32 v65, v223, v65, vcc
	v_cmp_le_i32_e32 vcc, v208, v174
	s_nop 1
	v_cndmask_b32_e32 v64, v223, v64, vcc
	v_cmp_le_i32_e32 vcc, v205, v174
	v_add_u32_e32 v205, 3, v208
	s_nop 0
	v_cndmask_b32_e32 v66, v223, v66, vcc
	v_cmp_le_i32_e32 vcc, v205, v174
	v_add_u32_e32 v205, 8, v208
	s_nop 0
	v_cndmask_b32_e32 v67, v223, v67, vcc
	v_cmp_le_i32_e32 vcc, v205, v174
	v_add_u32_e32 v205, 9, v208
	s_nop 0
	v_cndmask_b32_e32 v68, v223, v68, vcc
	v_cmp_le_i32_e32 vcc, v205, v174
	v_add_u32_e32 v205, 10, v208
	s_nop 0
	v_cndmask_b32_e32 v69, v223, v69, vcc
	v_cmp_le_i32_e32 vcc, v205, v174
	v_add_u32_e32 v205, 11, v208
	s_nop 0
	v_cndmask_b32_e32 v70, v223, v70, vcc
	v_cmp_le_i32_e32 vcc, v205, v174
	v_add_u32_e32 v205, 16, v208
	s_nop 0
	v_cndmask_b32_e32 v71, v223, v71, vcc
	v_cmp_le_i32_e32 vcc, v205, v174
	v_add_u32_e32 v205, 17, v208
	s_nop 0
	v_cndmask_b32_e32 v72, v223, v72, vcc
	v_cmp_le_i32_e32 vcc, v205, v174
	v_add_u32_e32 v205, 18, v208
	s_nop 0
	v_cndmask_b32_e32 v73, v223, v73, vcc
	v_cmp_le_i32_e32 vcc, v205, v174
	v_add_u32_e32 v205, 19, v208
	s_nop 0
	v_cndmask_b32_e32 v74, v223, v74, vcc
	v_cmp_le_i32_e32 vcc, v205, v174
	v_add_u32_e32 v205, 24, v208
	s_nop 0
	v_cndmask_b32_e32 v75, v223, v75, vcc
	v_cmp_le_i32_e32 vcc, v205, v174
	v_add_u32_e32 v205, 25, v208
	s_nop 0
	v_cndmask_b32_e32 v76, v223, v76, vcc
	v_cmp_le_i32_e32 vcc, v205, v174
	v_add_u32_e32 v205, 26, v208
	s_nop 0
	v_cndmask_b32_e32 v77, v223, v77, vcc
	v_cmp_le_i32_e32 vcc, v205, v174
	v_add_u32_e32 v205, 27, v208
	s_nop 0
	v_cndmask_b32_e32 v78, v223, v78, vcc
	v_cmp_le_i32_e32 vcc, v205, v174
	s_nop 1
	v_cndmask_b32_e32 v79, v223, v79, vcc
; DI float shx(float v, int o, int lane) { return __int_as_float(__builtin_amdgcn_ds_bpermute((lane ^ o) << 2, __float_as_int(v))); }
; DI int crow(int i, int hh) { return (i & 3) + 8 * (i >> 2) + 4 * hh; }
; #define MFMA32(a, b, c) __builtin_amdgcn_mfma_f32_32x32x16_bf16((a), (b), (c), 0, 0, 0)
; DI void attn_item(CArgs& a, LAS unsigned char* lds, int l, int b, int h, int qb, int tid_, int wave, int lane_) {
;     ...
;             if (j >= 4 * qb) {
; #pragma unroll
;                 for (int i = 0; i < 16; ++i) { const int key = 64 * j + 32 * kt + crow(i, hh); if (key > qloc) p[i] = -INFINITY; } }
;             float tmax = p[0];
; #pragma unroll
;             for (int i = 1; i < 16; ++i) tmax = fmaxf(tmax, p[i]);
;             tmax = fmaxf(tmax, shx(tmax, 32, lane));
;             const float m_new = fmaxf(m_run, tmax), alpha = __builtin_amdgcn_exp2f(m_run - m_new); m_run = m_new;
;             float rsum = 0.f;
; #pragma unroll
;             for (int i = 0; i < 16; ++i) { const float e = __builtin_amdgcn_exp2f(p[i] - m_new); p[i] = e; rsum += e; }
;             l_run = l_run * alpha + rsum;
;             if (__any(alpha != 1.f)) {
;                 if (hh == 0) scr[r] = alpha;
;                 asm volatile("s_waitcnt lgkmcnt(0)" ::: "memory");
; #pragma unroll
;                 for (int i = 0; i < 16; ++i) { const float ai = scr[crow(i, hh)]; o[0][i] *= ai; o[1][i] *= ai; o[2][i] *= ai; o[3][i] *= ai; }
;             }
;             const bf16x8 pa0 = packstep<0>(p), pa1 = packstep<1>(p);
; #pragma unroll
;             for (int vt = 0; vt < 4; ++vt) {
;                 o[vt] = MFMA32(pa0, lds_b128(Vs + (32 * vt + r) * 72 + 32 * kt + 8 * hh), o[vt]);
;                 o[vt] = MFMA32(pa1, lds_b128(Vs + (32 * vt + r) * 72 + 32 * kt + 16 + 8 * hh), o[vt]); }
;         }
.LBB0_323:
	v_max_f32_e32 v205, v65, v65
	v_max_f32_e32 v206, v64, v64
	v_max_f32_e32 v205, v206, v205
	s_waitcnt lgkmcnt(3)
	v_mfma_f32_32x32x16_bf16 v[82:97], v[216:219], v[114:117], v[82:97]
	ds_read_b128 v[216:219], v210 offset:22016
	v_max3_f32 v205, v205, v66, v67
	v_max3_f32 v205, v205, v68, v69
	v_max3_f32 v205, v205, v70, v71
	v_max3_f32 v205, v205, v72, v73
	s_waitcnt lgkmcnt(3)
	v_mfma_f32_32x32x16_bf16 v[82:97], v[238:241], v[118:121], v[82:97]
	ds_read_b128 v[238:241], v210 offset:22048
	v_max3_f32 v205, v205, v74, v75
	v_max3_f32 v205, v205, v76, v77
	v_max3_f32 v205, v205, v78, v79
	ds_bpermute_b32 v206, v198, v205
	s_waitcnt lgkmcnt(4)
	v_mfma_f32_32x32x16_bf16 v[82:97], v[242:245], v[122:125], v[82:97]
	ds_read_b128 v[242:245], v210 offset:22080
	s_waitcnt lgkmcnt(4)
	v_mfma_f32_32x32x16_bf16 v[82:97], v[246:249], v[126:129], v[82:97]
	ds_read_b128 v[246:249], v210 offset:22112
	s_waitcnt lgkmcnt(2)
	v_max3_f32 v211, v204, v205, v206
	v_sub_f32_e32 v204, v204, v211
	v_exp_f32_e32 v206, v204
	s_nop 0
	v_cmp_neq_f32_e32 vcc, 1.0, v206
	s_cbranch_vccz .LBB0_327
	s_and_saveexec_b64 s[2:3], s[6:7]
	ds_write_b32 v197, v206
	s_or_b64 exec, exec, s[2:3]
	s_waitcnt lgkmcnt(0)
	v_add_u32_e32 v204, s27, v80
	ds_read_b128 v[212:215], v204 offset:96
	ds_read_b128 v[234:237], v204 offset:64
	ds_read_b128 v[226:229], v204 offset:32
	ds_read_b128 v[230:233], v204
	s_waitcnt lgkmcnt(3)
	v_pk_mul_f32 v[12:13], v[12:13], v[212:213]
	s_waitcnt lgkmcnt(2)
	v_pk_mul_f32 v[8:9], v[8:9], v[234:235]
	s_waitcnt lgkmcnt(1)
	v_pk_mul_f32 v[4:5], v[4:5], v[226:227]
	v_pk_mul_f32 v[14:15], v[14:15], v[214:215]
	v_pk_mul_f32 v[10:11], v[10:11], v[236:237]
	v_pk_mul_f32 v[6:7], v[6:7], v[228:229]
	s_waitcnt lgkmcnt(0)
	v_pk_mul_f32 v[2:3], v[2:3], v[232:233]
	v_pk_mul_f32 v[0:1], v[0:1], v[230:231]
	v_pk_mul_f32 v[28:29], v[28:29], v[212:213]
	v_pk_mul_f32 v[24:25], v[24:25], v[234:235]
	v_pk_mul_f32 v[20:21], v[20:21], v[226:227]
	v_pk_mul_f32 v[30:31], v[30:31], v[214:215]
	v_pk_mul_f32 v[26:27], v[26:27], v[236:237]
	v_pk_mul_f32 v[22:23], v[22:23], v[228:229]
	v_pk_mul_f32 v[18:19], v[18:19], v[232:233]
	v_pk_mul_f32 v[16:17], v[16:17], v[230:231]
	v_pk_mul_f32 v[44:45], v[44:45], v[212:213]
	v_pk_mul_f32 v[40:41], v[40:41], v[234:235]
	v_pk_mul_f32 v[36:37], v[36:37], v[226:227]
	v_pk_mul_f32 v[46:47], v[46:47], v[214:215]
	v_pk_mul_f32 v[42:43], v[42:43], v[236:237]
	v_pk_mul_f32 v[38:39], v[38:39], v[228:229]
	v_pk_mul_f32 v[34:35], v[34:35], v[232:233]
	v_pk_mul_f32 v[32:33], v[32:33], v[230:231]
	v_pk_mul_f32 v[60:61], v[60:61], v[212:213]
	v_pk_mul_f32 v[56:57], v[56:57], v[234:235]
	v_pk_mul_f32 v[52:53], v[52:53], v[226:227]
	v_pk_mul_f32 v[62:63], v[62:63], v[214:215]
	v_pk_mul_f32 v[58:59], v[58:59], v[236:237]
	v_pk_mul_f32 v[54:55], v[54:55], v[228:229]
	v_pk_mul_f32 v[50:51], v[50:51], v[232:233]
	v_pk_mul_f32 v[48:49], v[48:49], v[230:231]
.LBB0_327:
	v_add3_u32 v205, s18, v199, v202
	v_add3_u32 v207, s18, v201, v202
	v_sub_f32_e32 v64, v64, v211
	v_exp_f32_e32 v212, v64
	v_sub_f32_e32 v64, v65, v211
	v_exp_f32_e32 v213, v64
	v_sub_f32_e32 v64, v66, v211
	v_exp_f32_e32 v214, v64
	v_sub_f32_e32 v64, v67, v211
	v_exp_f32_e32 v215, v64
	s_waitcnt lgkmcnt(4)
	v_mfma_f32_32x32x16_bf16 v[82:97], v[216:219], v[130:133], v[82:97]
	ds_read_b128 v[216:219], v205 offset:26624
	v_sub_f32_e32 v64, v68, v211
	v_exp_f32_e32 v225, v64
	v_sub_f32_e32 v64, v69, v211
	v_exp_f32_e32 v226, v64
	v_sub_f32_e32 v64, v70, v211
	v_exp_f32_e32 v227, v64
	v_sub_f32_e32 v64, v71, v211
	v_exp_f32_e32 v228, v64
	s_waitcnt lgkmcnt(4)
	v_mfma_f32_32x32x16_bf16 v[82:97], v[238:241], v[138:141], v[82:97]
	ds_read_b128 v[238:241], v207 offset:26624
	v_sub_f32_e32 v64, v72, v211
	v_exp_f32_e32 v229, v64
	v_sub_f32_e32 v64, v73, v211
	v_exp_f32_e32 v230, v64
	v_sub_f32_e32 v64, v74, v211
	v_exp_f32_e32 v231, v64
	v_sub_f32_e32 v64, v75, v211
	v_exp_f32_e32 v232, v64
	s_waitcnt lgkmcnt(3)
	v_mfma_f32_32x32x16_bf16 v[82:97], v[242:245], v[134:137], v[82:97]
	ds_read_b128 v[242:245], v205 offset:35840
	v_sub_f32_e32 v64, v76, v211
	v_exp_f32_e32 v233, v64
	v_sub_f32_e32 v64, v77, v211
	v_exp_f32_e32 v234, v64
	v_sub_f32_e32 v64, v78, v211
	v_exp_f32_e32 v235, v64
	v_sub_f32_e32 v72, v79, v211
	v_exp_f32_e32 v236, v72
	s_waitcnt lgkmcnt(3)
	v_mfma_f32_32x32x16_bf16 v[82:97], v[246:249], v[142:145], v[82:97]
	ds_read_b128 v[246:249], v205 offset:40448
	v_cvt_pk_bf16_f32 v64, v212, v213
	v_cvt_pk_bf16_f32 v65, v214, v215
	v_cvt_pk_bf16_f32 v66, v225, v226
	v_cvt_pk_bf16_f32 v67, v227, v228
	v_cvt_pk_bf16_f32 v72, v229, v230
	v_cvt_pk_bf16_f32 v73, v231, v232
	v_cvt_pk_bf16_f32 v74, v233, v234
	v_cvt_pk_bf16_f32 v75, v235, v236
	ds_read_b128 v[68:71], v205 offset:26656
	ds_read_b128 v[76:79], v207 offset:26656
	s_waitcnt lgkmcnt(5)
	v_mfma_f32_32x32x16_bf16 v[0:15], v[64:67], v[216:219], v[0:15]
	ds_read_b128 v[216:219], v205 offset:35872
	s_waitcnt lgkmcnt(5)
	v_mfma_f32_32x32x16_bf16 v[16:31], v[64:67], v[238:241], v[16:31]
	ds_read_b128 v[238:241], v205 offset:40480
	s_waitcnt lgkmcnt(5)
	v_mfma_f32_32x32x16_bf16 v[32:47], v[64:67], v[242:245], v[32:47]
	s_waitcnt lgkmcnt(4)
	v_mfma_f32_32x32x16_bf16 v[48:63], v[64:67], v[246:249], v[48:63]
	s_andn2_b64 vcc, exec, s[0:1]
	s_cbranch_vccnz .LBB0_329
	v_add_u32_e32 v204, 32, v208
	v_cmp_le_i32_e32 vcc, v204, v174
	v_add_u32_e32 v204, 33, v208
	s_nop 0
	v_cndmask_b32_e32 v82, v223, v82, vcc
	v_cmp_le_i32_e32 vcc, v204, v174
	v_add_u32_e32 v204, 34, v208
	s_nop 0
	v_cndmask_b32_e32 v83, v223, v83, vcc
	v_cmp_le_i32_e32 vcc, v204, v174
	v_add_u32_e32 v204, 35, v208
	s_nop 0
	v_cndmask_b32_e32 v84, v223, v84, vcc
	v_cmp_le_i32_e32 vcc, v204, v174
	v_add_u32_e32 v204, 40, v208
	s_nop 0
	v_cndmask_b32_e32 v85, v223, v85, vcc
	v_cmp_le_i32_e32 vcc, v204, v174
	v_add_u32_e32 v204, 41, v208
	s_nop 0
	v_cndmask_b32_e32 v86, v223, v86, vcc
	v_cmp_le_i32_e32 vcc, v204, v174
	v_add_u32_e32 v204, 42, v208
	s_nop 0
	v_cndmask_b32_e32 v87, v223, v87, vcc
	v_cmp_le_i32_e32 vcc, v204, v174
	v_add_u32_e32 v204, 43, v208
	s_nop 0
	v_cndmask_b32_e32 v88, v223, v88, vcc
	v_cmp_le_i32_e32 vcc, v204, v174
	v_add_u32_e32 v204, 48, v208
	s_nop 0
	v_cndmask_b32_e32 v89, v223, v89, vcc
	v_cmp_le_i32_e32 vcc, v204, v174
	v_add_u32_e32 v204, 49, v208
	s_nop 0
	v_cndmask_b32_e32 v90, v223, v90, vcc
	v_cmp_le_i32_e32 vcc, v204, v174
	v_add_u32_e32 v204, 50, v208
	s_nop 0
	v_cndmask_b32_e32 v91, v223, v91, vcc
	v_cmp_le_i32_e32 vcc, v204, v174
	v_add_u32_e32 v204, 51, v208
	s_nop 0
	v_cndmask_b32_e32 v92, v223, v92, vcc
	v_cmp_le_i32_e32 vcc, v204, v174
	v_add_u32_e32 v204, 56, v208
	s_nop 0
	v_cndmask_b32_e32 v93, v223, v93, vcc
	v_cmp_le_i32_e32 vcc, v204, v174
	v_add_u32_e32 v204, 57, v208
	s_nop 0
	v_cndmask_b32_e32 v94, v223, v94, vcc
	v_cmp_le_i32_e32 vcc, v204, v174
	v_add_u32_e32 v204, 58, v208
	s_nop 0
	v_cndmask_b32_e32 v95, v223, v95, vcc
	v_cmp_le_i32_e32 vcc, v204, v174
	v_add_u32_e32 v204, 59, v208
	s_nop 0
	v_cndmask_b32_e32 v96, v223, v96, vcc
	v_cmp_le_i32_e32 vcc, v204, v174
	s_nop 1
	v_cndmask_b32_e32 v97, v223, v97, vcc
; DI float shx(float v, int o, int lane) { return __int_as_float(__builtin_amdgcn_ds_bpermute((lane ^ o) << 2, __float_as_int(v))); }
; DI int crow(int i, int hh) { return (i & 3) + 8 * (i >> 2) + 4 * hh; }
; #define MFMA32(a, b, c) __builtin_amdgcn_mfma_f32_32x32x16_bf16((a), (b), (c), 0, 0, 0)
; DI void attn_item(CArgs& a, LAS unsigned char* lds, int l, int b, int h, int qb, int tid_, int wave, int lane_) {
;     ...
;             float tmax = p[0];
; #pragma unroll
;             for (int i = 1; i < 16; ++i) tmax = fmaxf(tmax, p[i]);
;             tmax = fmaxf(tmax, shx(tmax, 32, lane));
;             const float m_new = fmaxf(m_run, tmax), alpha = __builtin_amdgcn_exp2f(m_run - m_new); m_run = m_new;
;             float rsum = 0.f;
; #pragma unroll
;             for (int i = 0; i < 16; ++i) { const float e = __builtin_amdgcn_exp2f(p[i] - m_new); p[i] = e; rsum += e; }
;             l_run = l_run * alpha + rsum;
;             if (__any(alpha != 1.f)) {
;                 if (hh == 0) scr[r] = alpha;
;                 asm volatile("s_waitcnt lgkmcnt(0)" ::: "memory");
; #pragma unroll
;                 for (int i = 0; i < 16; ++i) { const float ai = scr[crow(i, hh)]; o[0][i] *= ai; o[1][i] *= ai; o[2][i] *= ai; o[3][i] *= ai; }
;             }
;             const bf16x8 pa0 = packstep<0>(p), pa1 = packstep<1>(p);
; #pragma unroll
;             for (int vt = 0; vt < 4; ++vt) {
;                 o[vt] = MFMA32(pa0, lds_b128(Vs + (32 * vt + r) * 72 + 32 * kt + 8 * hh), o[vt]);
;                 o[vt] = MFMA32(pa1, lds_b128(Vs + (32 * vt + r) * 72 + 32 * kt + 16 + 8 * hh), o[vt]); }
.LBB0_329:
	v_max_f32_e32 v204, v83, v83
	v_max_f32_e32 v208, v82, v82
	v_max_f32_e32 v204, v208, v204
	s_waitcnt lgkmcnt(3)
	v_mfma_f32_32x32x16_bf16 v[0:15], v[72:75], v[68:71], v[0:15]
	v_max3_f32 v204, v204, v84, v85
	v_max3_f32 v204, v204, v86, v87
	v_max3_f32 v204, v204, v88, v89
	v_max3_f32 v204, v204, v90, v91
	s_waitcnt lgkmcnt(2)
	v_mfma_f32_32x32x16_bf16 v[16:31], v[72:75], v[76:79], v[16:31]
	v_max3_f32 v204, v204, v92, v93
	v_max3_f32 v204, v204, v94, v95
	v_max3_f32 v204, v204, v96, v97
	ds_bpermute_b32 v208, v198, v204
	s_waitcnt lgkmcnt(2)
	v_mfma_f32_32x32x16_bf16 v[32:47], v[72:75], v[216:219], v[32:47]
	s_waitcnt lgkmcnt(1)
	v_mfma_f32_32x32x16_bf16 v[48:63], v[72:75], v[238:241], v[48:63]
	s_waitcnt lgkmcnt(0)
	v_max3_f32 v204, v211, v204, v208
	v_sub_f32_e32 v208, v211, v204
	v_exp_f32_e32 v208, v208
	s_nop 0
	v_cmp_neq_f32_e32 vcc, 1.0, v208
	s_cbranch_vccz .LBB0_333
	s_and_saveexec_b64 s[0:1], s[6:7]
	ds_write_b32 v197, v208
	s_or_b64 exec, exec, s[0:1]
	s_waitcnt lgkmcnt(0)
	v_add_u32_e32 v209, s27, v80
	ds_read_b128 v[216:219], v209 offset:96
	ds_read_b128 v[238:241], v209 offset:64
	ds_read_b128 v[242:245], v209 offset:32
	ds_read_b128 v[246:249], v209
	s_waitcnt lgkmcnt(3)
	v_pk_mul_f32 v[12:13], v[12:13], v[216:217]
	s_waitcnt lgkmcnt(2)
	v_pk_mul_f32 v[8:9], v[8:9], v[238:239]
	s_waitcnt lgkmcnt(1)
	v_pk_mul_f32 v[4:5], v[4:5], v[242:243]
	v_pk_mul_f32 v[14:15], v[14:15], v[218:219]
	v_pk_mul_f32 v[10:11], v[10:11], v[240:241]
	v_pk_mul_f32 v[6:7], v[6:7], v[244:245]
	s_waitcnt lgkmcnt(0)
	v_pk_mul_f32 v[2:3], v[2:3], v[248:249]
	v_pk_mul_f32 v[0:1], v[0:1], v[246:247]
	v_pk_mul_f32 v[28:29], v[28:29], v[216:217]
	v_pk_mul_f32 v[24:25], v[24:25], v[238:239]
	v_pk_mul_f32 v[20:21], v[20:21], v[242:243]
	v_pk_mul_f32 v[30:31], v[30:31], v[218:219]
	v_pk_mul_f32 v[26:27], v[26:27], v[240:241]
	v_pk_mul_f32 v[22:23], v[22:23], v[244:245]
	v_pk_mul_f32 v[18:19], v[18:19], v[248:249]
	v_pk_mul_f32 v[16:17], v[16:17], v[246:247]
	v_pk_mul_f32 v[44:45], v[44:45], v[216:217]
	v_pk_mul_f32 v[40:41], v[40:41], v[238:239]
	v_pk_mul_f32 v[36:37], v[36:37], v[242:243]
	v_pk_mul_f32 v[46:47], v[46:47], v[218:219]
	v_pk_mul_f32 v[42:43], v[42:43], v[240:241]
	v_pk_mul_f32 v[38:39], v[38:39], v[244:245]
	v_pk_mul_f32 v[34:35], v[34:35], v[248:249]
	v_pk_mul_f32 v[32:33], v[32:33], v[246:247]
	v_pk_mul_f32 v[60:61], v[60:61], v[216:217]
	v_pk_mul_f32 v[56:57], v[56:57], v[238:239]
	v_pk_mul_f32 v[52:53], v[52:53], v[242:243]
	v_pk_mul_f32 v[62:63], v[62:63], v[218:219]
	v_pk_mul_f32 v[58:59], v[58:59], v[240:241]
	v_pk_mul_f32 v[54:55], v[54:55], v[244:245]
	v_pk_mul_f32 v[50:51], v[50:51], v[248:249]
	v_pk_mul_f32 v[48:49], v[48:49], v[246:247]
.LBB0_333:
	ds_read_b128 v[242:245], v205 offset:26688
	ds_read_b128 v[246:249], v207 offset:26688
	ds_read_b128 v[216:219], v205 offset:35904
	ds_read_b128 v[238:241], v205 offset:40512
	v_add_f32_e32 v209, 0, v212
	v_add_f32_e32 v209, v213, v209
	v_add_f32_e32 v209, v214, v209
	v_add_f32_e32 v209, v215, v209
	v_add_f32_e32 v209, v225, v209
	v_add_f32_e32 v209, v226, v209
	v_add_f32_e32 v209, v227, v209
	v_add_f32_e32 v209, v228, v209
	v_add_f32_e32 v209, v229, v209
	v_add_f32_e32 v209, v230, v209
	v_add_f32_e32 v209, v231, v209
	v_add_f32_e32 v209, v232, v209
	v_sub_f32_e32 v82, v82, v204
	v_add_f32_e32 v209, v233, v209
	v_exp_f32_e32 v82, v82
	v_sub_f32_e32 v83, v83, v204
	v_add_f32_e32 v209, v234, v209
	v_exp_f32_e32 v83, v83
	v_sub_f32_e32 v84, v84, v204
	v_add_f32_e32 v209, v235, v209
	v_exp_f32_e32 v84, v84
	v_sub_f32_e32 v85, v85, v204
	v_add_f32_e32 v209, v236, v209
	v_exp_f32_e32 v85, v85
	v_sub_f32_e32 v86, v86, v204
	v_fmac_f32_e32 v209, v203, v206
	v_add_f32_e32 v203, 0, v82
	v_exp_f32_e32 v86, v86
	v_sub_f32_e32 v87, v87, v204
	v_add_f32_e32 v203, v83, v203
	v_exp_f32_e32 v87, v87
	v_sub_f32_e32 v88, v88, v204
	v_add_f32_e32 v203, v84, v203
	v_exp_f32_e32 v88, v88
	v_sub_f32_e32 v89, v89, v204
	v_add_f32_e32 v203, v85, v203
	v_exp_f32_e32 v89, v89
	v_sub_f32_e32 v90, v90, v204
	v_add_f32_e32 v203, v86, v203
	v_exp_f32_e32 v90, v90
	v_sub_f32_e32 v91, v91, v204
	v_add_f32_e32 v203, v87, v203
	v_exp_f32_e32 v91, v91
	v_sub_f32_e32 v92, v92, v204
	v_add_f32_e32 v203, v88, v203
	v_exp_f32_e32 v92, v92
	v_sub_f32_e32 v93, v93, v204
	v_add_f32_e32 v203, v89, v203
	v_exp_f32_e32 v93, v93
	v_sub_f32_e32 v94, v94, v204
	v_add_f32_e32 v203, v90, v203
	v_exp_f32_e32 v94, v94
	v_sub_f32_e32 v95, v95, v204
	v_add_f32_e32 v203, v91, v203
	v_exp_f32_e32 v95, v95
	v_sub_f32_e32 v96, v96, v204
	v_add_f32_e32 v203, v92, v203
	v_exp_f32_e32 v96, v96
	v_sub_f32_e32 v97, v97, v204
	v_add_f32_e32 v203, v93, v203
	v_exp_f32_e32 v97, v97
	v_add_f32_e32 v203, v94, v203
	v_add_f32_e32 v203, v95, v203
	v_add_f32_e32 v203, v96, v203
	v_cvt_pk_bf16_f32 v82, v82, v83
	v_cvt_pk_bf16_f32 v83, v84, v85
	v_cvt_pk_bf16_f32 v84, v86, v87
	v_cvt_pk_bf16_f32 v85, v88, v89
	v_add_f32_e32 v203, v97, v203
	v_cvt_pk_bf16_f32 v86, v90, v91
	v_cvt_pk_bf16_f32 v87, v92, v93
	v_cvt_pk_bf16_f32 v88, v94, v95
	v_cvt_pk_bf16_f32 v89, v96, v97
	ds_read_b128 v[90:93], v205 offset:26720
	ds_read_b128 v[94:97], v207 offset:26720
	s_waitcnt lgkmcnt(5)
	v_mfma_f32_32x32x16_bf16 v[0:15], v[82:85], v[242:245], v[0:15]
	ds_read_b128 v[242:245], v205 offset:35936
	s_add_i32 s4, s4, 64
	s_mov_b64 s[0:1], 0x2000
	v_fmac_f32_e32 v203, v209, v208
	s_waitcnt lgkmcnt(5)
	v_mfma_f32_32x32x16_bf16 v[16:31], v[82:85], v[246:249], v[16:31]
	ds_read_b128 v[246:249], v205 offset:40544
	v_lshl_add_u64 v[176:177], v[176:177], 0, s[68:69]
	v_lshl_add_u64 v[178:179], v[178:179], 0, s[68:69]
	s_waitcnt lgkmcnt(5)
	v_mfma_f32_32x32x16_bf16 v[32:47], v[82:85], v[216:219], v[32:47]
	v_lshl_add_u64 v[180:181], v[180:181], 0, s[0:1]
	v_lshl_add_u64 v[182:183], v[182:183], 0, s[58:59]
	s_waitcnt lgkmcnt(4)
	v_mfma_f32_32x32x16_bf16 v[48:63], v[82:85], v[238:241], v[48:63]
	v_lshl_add_u64 v[184:185], v[184:185], 0, s[58:59]
	s_cmp_eq_u32 s16, s4
	s_waitcnt lgkmcnt(3)
	v_mfma_f32_32x32x16_bf16 v[0:15], v[86:89], v[90:93], v[0:15]
	s_waitcnt lgkmcnt(2)
	v_mfma_f32_32x32x16_bf16 v[16:31], v[86:89], v[94:97], v[16:31]
	s_waitcnt lgkmcnt(0)
	s_barrier
	v_mfma_f32_32x32x16_bf16 v[32:47], v[86:89], v[242:245], v[32:47]
	v_mfma_f32_32x32x16_bf16 v[48:63], v[86:89], v[246:249], v[48:63]
	s_cbranch_scc1 .LBB0_335
	s_mov_b32 s2, s17
	s_branch .LBB0_317
